# in-projection k-loop hand-rescheduled: read->write barrier moved up (10 fragment quads), LDS stores behind last MFMAs, global loads spread over MFMA pairs via SGPR bases; softmax cross-half max via v_
# speedup vs baseline: 1.0333x; 1.0102x over previous
; DI void softmax_pv(f32x16 (&sa)[2], f32x16 (&O)[4], float& m, float& l, const char* sV, int lr, int lh, bool first) {
;   float t0 = fmaxf(fmaxf(sa[0][0], sa[0][1]), sa[0][2]);
;   float t1 = fmaxf(fmaxf(sa[1][0], sa[1][1]), sa[1][2]);
; #pragma unroll
;   for (int i = 3; i < 15; i += 2) {
;     t0 = fmaxf(fmaxf(t0, sa[0][i]), sa[0][i + 1]);
;     t1 = fmaxf(fmaxf(t1, sa[1][i]), sa[1][i + 1]);
;   }
;   float tmax = fmaxf(fmaxf(t0, t1), fmaxf(sa[0][15], sa[1][15]));
;   tmax = fmaxf(tmax, __shfl_xor(tmax, 32, 64));
;   if (first || __any(tmax > SM_THR)) {
;     asm volatile("; rescale" ::: "memory");
;     const float delta = first ? tmax : fmaxf(tmax, 0.f);
;     const float alpha = __builtin_amdgcn_exp2f(-delta);
;     m += delta;
;     l *= alpha;
; #pragma unroll
;     for (int d = 0; d < 4; ++d)
; #pragma unroll
;       for (int i = 0; i < 16; ++i) O[d][i] *= alpha;
; #pragma unroll
;     for (int i = 0; i < 16; ++i) { sa[0][i] -= delta; sa[1][i] -= delta; }
;   }
.LBB0_130:
	v_max3_f32 v172, v80, v81, v82
	s_nop 1
	v_max3_f32 v173, v64, v65, v66
	v_max3_f32 v172, v172, v83, v84
	v_max3_f32 v173, v173, v67, v68
	v_max3_f32 v172, v172, v85, v86
	v_max3_f32 v173, v173, v69, v70
	v_max3_f32 v172, v172, v87, v88
	v_max3_f32 v173, v173, v71, v72
	v_max3_f32 v172, v172, v89, v90
	v_max3_f32 v173, v173, v73, v74
	v_max3_f32 v172, v172, v91, v92
	v_max3_f32 v173, v173, v75, v76
	v_max_f32_e32 v174, v79, v79
	v_max_f32_e32 v175, v95, v95
	v_max3_f32 v172, v172, v93, v94
	v_max3_f32 v173, v173, v77, v78
	v_max_f32_e32 v174, v175, v174
	v_max3_f32 v172, v172, v173, v174
	v_mov_b32_e32 v173, v172
	s_mov_b32 s10, 0x41000000
	s_nop 0
	v_permlane32_swap_b32_e32 v173, v172
	v_max_f32_e32 v172, v172, v173
	v_cmp_lt_f32_e32 vcc, s10, v172
	s_cbranch_vccz .LBB0_132
	v_max_f32_e32 v172, v172, v172
	v_max_f32_e32 v172, 0, v172
	v_exp_f32_e64 v174, -v172
	v_add_f32_e32 v166, v166, v172
	v_pk_add_f32 v[80:81], v[80:81], v[172:173] op_sel_hi:[1,0] neg_lo:[0,1] neg_hi:[0,1]
	v_mul_f32_e32 v163, v163, v174
	v_pk_mul_f32 v[62:63], v[62:63], v[174:175] op_sel_hi:[1,0]
	v_pk_mul_f32 v[60:61], v[60:61], v[174:175] op_sel_hi:[1,0]
	v_pk_mul_f32 v[58:59], v[58:59], v[174:175] op_sel_hi:[1,0]
	v_pk_mul_f32 v[56:57], v[56:57], v[174:175] op_sel_hi:[1,0]
	v_pk_mul_f32 v[54:55], v[54:55], v[174:175] op_sel_hi:[1,0]
	v_pk_mul_f32 v[52:53], v[52:53], v[174:175] op_sel_hi:[1,0]
	v_pk_mul_f32 v[50:51], v[50:51], v[174:175] op_sel_hi:[1,0]
	v_pk_mul_f32 v[48:49], v[48:49], v[174:175] op_sel_hi:[1,0]
	v_pk_mul_f32 v[46:47], v[46:47], v[174:175] op_sel_hi:[1,0]
	v_pk_mul_f32 v[44:45], v[44:45], v[174:175] op_sel_hi:[1,0]
	v_pk_mul_f32 v[42:43], v[42:43], v[174:175] op_sel_hi:[1,0]
	v_pk_mul_f32 v[40:41], v[40:41], v[174:175] op_sel_hi:[1,0]
	v_pk_mul_f32 v[38:39], v[38:39], v[174:175] op_sel_hi:[1,0]
	v_pk_mul_f32 v[36:37], v[36:37], v[174:175] op_sel_hi:[1,0]
	v_pk_mul_f32 v[34:35], v[34:35], v[174:175] op_sel_hi:[1,0]
	v_pk_mul_f32 v[32:33], v[32:33], v[174:175] op_sel_hi:[1,0]
	v_pk_mul_f32 v[30:31], v[30:31], v[174:175] op_sel_hi:[1,0]
	v_pk_mul_f32 v[28:29], v[28:29], v[174:175] op_sel_hi:[1,0]
	v_pk_mul_f32 v[26:27], v[26:27], v[174:175] op_sel_hi:[1,0]
	v_pk_mul_f32 v[24:25], v[24:25], v[174:175] op_sel_hi:[1,0]
	v_pk_mul_f32 v[22:23], v[22:23], v[174:175] op_sel_hi:[1,0]
	v_pk_mul_f32 v[20:21], v[20:21], v[174:175] op_sel_hi:[1,0]
	v_pk_mul_f32 v[18:19], v[18:19], v[174:175] op_sel_hi:[1,0]
	v_pk_mul_f32 v[16:17], v[16:17], v[174:175] op_sel_hi:[1,0]
	v_pk_mul_f32 v[14:15], v[14:15], v[174:175] op_sel_hi:[1,0]
	v_pk_mul_f32 v[12:13], v[12:13], v[174:175] op_sel_hi:[1,0]
	v_pk_mul_f32 v[10:11], v[10:11], v[174:175] op_sel_hi:[1,0]
	v_pk_mul_f32 v[8:9], v[8:9], v[174:175] op_sel_hi:[1,0]
	v_pk_mul_f32 v[6:7], v[6:7], v[174:175] op_sel_hi:[1,0]
	v_pk_mul_f32 v[4:5], v[4:5], v[174:175] op_sel_hi:[1,0]
	v_pk_mul_f32 v[2:3], v[2:3], v[174:175] op_sel_hi:[1,0]
	v_pk_mul_f32 v[0:1], v[0:1], v[174:175] op_sel_hi:[1,0]
	v_pk_add_f32 v[64:65], v[64:65], v[172:173] op_sel_hi:[1,0] neg_lo:[0,1] neg_hi:[0,1]
	v_pk_add_f32 v[82:83], v[82:83], v[172:173] op_sel_hi:[1,0] neg_lo:[0,1] neg_hi:[0,1]
	v_pk_add_f32 v[66:67], v[66:67], v[172:173] op_sel_hi:[1,0] neg_lo:[0,1] neg_hi:[0,1]
	v_pk_add_f32 v[84:85], v[84:85], v[172:173] op_sel_hi:[1,0] neg_lo:[0,1] neg_hi:[0,1]
	v_pk_add_f32 v[68:69], v[68:69], v[172:173] op_sel_hi:[1,0] neg_lo:[0,1] neg_hi:[0,1]
	v_pk_add_f32 v[86:87], v[86:87], v[172:173] op_sel_hi:[1,0] neg_lo:[0,1] neg_hi:[0,1]
	v_pk_add_f32 v[70:71], v[70:71], v[172:173] op_sel_hi:[1,0] neg_lo:[0,1] neg_hi:[0,1]
	v_pk_add_f32 v[88:89], v[88:89], v[172:173] op_sel_hi:[1,0] neg_lo:[0,1] neg_hi:[0,1]
	v_pk_add_f32 v[72:73], v[72:73], v[172:173] op_sel_hi:[1,0] neg_lo:[0,1] neg_hi:[0,1]
	v_pk_add_f32 v[90:91], v[90:91], v[172:173] op_sel_hi:[1,0] neg_lo:[0,1] neg_hi:[0,1]
	v_pk_add_f32 v[74:75], v[74:75], v[172:173] op_sel_hi:[1,0] neg_lo:[0,1] neg_hi:[0,1]
	v_pk_add_f32 v[92:93], v[92:93], v[172:173] op_sel_hi:[1,0] neg_lo:[0,1] neg_hi:[0,1]
	v_pk_add_f32 v[76:77], v[76:77], v[172:173] op_sel_hi:[1,0] neg_lo:[0,1] neg_hi:[0,1]
	v_pk_add_f32 v[94:95], v[94:95], v[172:173] op_sel_hi:[1,0] neg_lo:[0,1] neg_hi:[0,1]
	v_pk_add_f32 v[78:79], v[78:79], v[172:173] op_sel_hi:[1,0] neg_lo:[0,1] neg_hi:[0,1]

; DI void softmax_pv(f32x16 (&sa)[2], f32x16 (&O)[4], float& m, float& l, const char* sV, int lr, int lh, bool first) {
;   float t0 = fmaxf(fmaxf(sa[0][0], sa[0][1]), sa[0][2]);
;   float t1 = fmaxf(fmaxf(sa[1][0], sa[1][1]), sa[1][2]);
; #pragma unroll
;   for (int i = 3; i < 15; i += 2) {
;     t0 = fmaxf(fmaxf(t0, sa[0][i]), sa[0][i + 1]);
;     t1 = fmaxf(fmaxf(t1, sa[1][i]), sa[1][i + 1]);
;   }
;   float tmax = fmaxf(fmaxf(t0, t1), fmaxf(sa[0][15], sa[1][15]));
;   tmax = fmaxf(tmax, __shfl_xor(tmax, 32, 64));
;   if (first || __any(tmax > SM_THR)) {
;     asm volatile("; rescale" ::: "memory");
;     const float delta = first ? tmax : fmaxf(tmax, 0.f);
;     const float alpha = __builtin_amdgcn_exp2f(-delta);
;     m += delta;
;     l *= alpha;
; #pragma unroll
;     for (int d = 0; d < 4; ++d)
; #pragma unroll
;       for (int i = 0; i < 16; ++i) O[d][i] *= alpha;
; #pragma unroll
;     for (int i = 0; i < 16; ++i) { sa[0][i] -= delta; sa[1][i] -= delta; }
;   }
.LBB0_158:
	s_nop 3
	v_max3_f32 v184, v80, v81, v82
	s_nop 0
	v_max3_f32 v202, v64, v65, v66
	v_max3_f32 v184, v184, v83, v84
	v_max3_f32 v202, v202, v67, v68
	v_max3_f32 v184, v184, v85, v86
	v_max3_f32 v202, v202, v69, v70
	v_max3_f32 v184, v184, v87, v88
	v_max3_f32 v202, v202, v71, v72
	v_max3_f32 v184, v184, v89, v90
	v_max3_f32 v202, v202, v73, v74
	v_max3_f32 v184, v184, v91, v92
	v_max3_f32 v202, v202, v75, v76
	v_max_f32_e32 v203, v79, v79
	v_max_f32_e32 v204, v95, v95
	v_max3_f32 v184, v184, v93, v94
	v_max3_f32 v202, v202, v77, v78
	v_max_f32_e32 v203, v204, v203
	v_max3_f32 v184, v184, v202, v203
	v_mov_b32_e32 v202, v184
	s_nop 1
	v_permlane32_swap_b32_e32 v202, v184
	v_max_f32_e32 v184, v184, v202
	v_cmp_lt_f32_e32 vcc, s93, v184
	s_cbranch_vccz .LBB0_160
	v_max_f32_e32 v184, v184, v184
	v_max_f32_e32 v184, 0, v184
	v_exp_f32_e64 v202, -v184
	v_add_f32_e32 v226, v226, v184
	v_pk_add_f32 v[80:81], v[80:81], v[184:185] op_sel_hi:[1,0] neg_lo:[0,1] neg_hi:[0,1]
	v_mul_f32_e32 v222, v222, v202
	v_pk_mul_f32 v[62:63], v[62:63], v[202:203] op_sel_hi:[1,0]
	v_pk_mul_f32 v[60:61], v[60:61], v[202:203] op_sel_hi:[1,0]
	v_pk_mul_f32 v[58:59], v[58:59], v[202:203] op_sel_hi:[1,0]
	v_pk_mul_f32 v[56:57], v[56:57], v[202:203] op_sel_hi:[1,0]
	v_pk_mul_f32 v[54:55], v[54:55], v[202:203] op_sel_hi:[1,0]
	v_pk_mul_f32 v[52:53], v[52:53], v[202:203] op_sel_hi:[1,0]
	v_pk_mul_f32 v[50:51], v[50:51], v[202:203] op_sel_hi:[1,0]
	v_pk_mul_f32 v[48:49], v[48:49], v[202:203] op_sel_hi:[1,0]
	v_pk_mul_f32 v[46:47], v[46:47], v[202:203] op_sel_hi:[1,0]
	v_pk_mul_f32 v[44:45], v[44:45], v[202:203] op_sel_hi:[1,0]
	v_pk_mul_f32 v[42:43], v[42:43], v[202:203] op_sel_hi:[1,0]
	v_pk_mul_f32 v[40:41], v[40:41], v[202:203] op_sel_hi:[1,0]
	v_pk_mul_f32 v[38:39], v[38:39], v[202:203] op_sel_hi:[1,0]
	v_pk_mul_f32 v[36:37], v[36:37], v[202:203] op_sel_hi:[1,0]
	v_pk_mul_f32 v[34:35], v[34:35], v[202:203] op_sel_hi:[1,0]
	v_pk_mul_f32 v[32:33], v[32:33], v[202:203] op_sel_hi:[1,0]
	v_pk_mul_f32 v[30:31], v[30:31], v[202:203] op_sel_hi:[1,0]
	v_pk_mul_f32 v[28:29], v[28:29], v[202:203] op_sel_hi:[1,0]
	v_pk_mul_f32 v[26:27], v[26:27], v[202:203] op_sel_hi:[1,0]
	v_pk_mul_f32 v[24:25], v[24:25], v[202:203] op_sel_hi:[1,0]
	v_pk_mul_f32 v[22:23], v[22:23], v[202:203] op_sel_hi:[1,0]
	v_pk_mul_f32 v[20:21], v[20:21], v[202:203] op_sel_hi:[1,0]
	v_pk_mul_f32 v[18:19], v[18:19], v[202:203] op_sel_hi:[1,0]
	v_pk_mul_f32 v[16:17], v[16:17], v[202:203] op_sel_hi:[1,0]
	v_pk_mul_f32 v[14:15], v[14:15], v[202:203] op_sel_hi:[1,0]
	v_pk_mul_f32 v[12:13], v[12:13], v[202:203] op_sel_hi:[1,0]
	v_pk_mul_f32 v[10:11], v[10:11], v[202:203] op_sel_hi:[1,0]
	v_pk_mul_f32 v[8:9], v[8:9], v[202:203] op_sel_hi:[1,0]
	v_pk_mul_f32 v[6:7], v[6:7], v[202:203] op_sel_hi:[1,0]
	v_pk_mul_f32 v[4:5], v[4:5], v[202:203] op_sel_hi:[1,0]
	v_pk_mul_f32 v[2:3], v[2:3], v[202:203] op_sel_hi:[1,0]
	v_pk_mul_f32 v[0:1], v[0:1], v[202:203] op_sel_hi:[1,0]
	v_pk_add_f32 v[64:65], v[64:65], v[184:185] op_sel_hi:[1,0] neg_lo:[0,1] neg_hi:[0,1]
	v_pk_add_f32 v[82:83], v[82:83], v[184:185] op_sel_hi:[1,0] neg_lo:[0,1] neg_hi:[0,1]
	v_pk_add_f32 v[66:67], v[66:67], v[184:185] op_sel_hi:[1,0] neg_lo:[0,1] neg_hi:[0,1]
	v_pk_add_f32 v[84:85], v[84:85], v[184:185] op_sel_hi:[1,0] neg_lo:[0,1] neg_hi:[0,1]
	v_pk_add_f32 v[68:69], v[68:69], v[184:185] op_sel_hi:[1,0] neg_lo:[0,1] neg_hi:[0,1]
	v_pk_add_f32 v[86:87], v[86:87], v[184:185] op_sel_hi:[1,0] neg_lo:[0,1] neg_hi:[0,1]
	v_pk_add_f32 v[70:71], v[70:71], v[184:185] op_sel_hi:[1,0] neg_lo:[0,1] neg_hi:[0,1]
	v_pk_add_f32 v[88:89], v[88:89], v[184:185] op_sel_hi:[1,0] neg_lo:[0,1] neg_hi:[0,1]
	v_pk_add_f32 v[72:73], v[72:73], v[184:185] op_sel_hi:[1,0] neg_lo:[0,1] neg_hi:[0,1]
	v_pk_add_f32 v[90:91], v[90:91], v[184:185] op_sel_hi:[1,0] neg_lo:[0,1] neg_hi:[0,1]
	v_pk_add_f32 v[74:75], v[74:75], v[184:185] op_sel_hi:[1,0] neg_lo:[0,1] neg_hi:[0,1]
	v_pk_add_f32 v[92:93], v[92:93], v[184:185] op_sel_hi:[1,0] neg_lo:[0,1] neg_hi:[0,1]
	v_pk_add_f32 v[76:77], v[76:77], v[184:185] op_sel_hi:[1,0] neg_lo:[0,1] neg_hi:[0,1]
	v_pk_add_f32 v[94:95], v[94:95], v[184:185] op_sel_hi:[1,0] neg_lo:[0,1] neg_hi:[0,1]
	v_pk_add_f32 v[78:79], v[78:79], v[184:185] op_sel_hi:[1,0] neg_lo:[0,1] neg_hi:[0,1]

; DI void softmax_pv(f32x16 (&sa)[2], f32x16 (&O)[4], float& m, float& l, const char* sV, int lr, int lh, bool first) {
;   float t0 = fmaxf(fmaxf(sa[0][0], sa[0][1]), sa[0][2]);
;   float t1 = fmaxf(fmaxf(sa[1][0], sa[1][1]), sa[1][2]);
; #pragma unroll
;   for (int i = 3; i < 15; i += 2) {
;     t0 = fmaxf(fmaxf(t0, sa[0][i]), sa[0][i + 1]);
;     t1 = fmaxf(fmaxf(t1, sa[1][i]), sa[1][i + 1]);
;   }
;   float tmax = fmaxf(fmaxf(t0, t1), fmaxf(sa[0][15], sa[1][15]));
;   tmax = fmaxf(tmax, __shfl_xor(tmax, 32, 64));
;   if (first || __any(tmax > SM_THR)) {
;     asm volatile("; rescale" ::: "memory");
;     const float delta = first ? tmax : fmaxf(tmax, 0.f);
;     const float alpha = __builtin_amdgcn_exp2f(-delta);
;     m += delta;
;     l *= alpha;
; #pragma unroll
;     for (int d = 0; d < 4; ++d)
; #pragma unroll
;       for (int i = 0; i < 16; ++i) O[d][i] *= alpha;
; #pragma unroll
;     for (int i = 0; i < 16; ++i) { sa[0][i] -= delta; sa[1][i] -= delta; }
;   }
.LBB0_231:
	s_nop 3
	v_max3_f32 v184, v80, v81, v82
	s_nop 0
	v_max3_f32 v202, v64, v65, v66
	v_max3_f32 v184, v184, v83, v84
	v_max3_f32 v202, v202, v67, v68
	v_max3_f32 v184, v184, v85, v86
	v_max3_f32 v202, v202, v69, v70
	v_max3_f32 v184, v184, v87, v88
	v_max3_f32 v202, v202, v71, v72
	v_max3_f32 v184, v184, v89, v90
	v_max3_f32 v202, v202, v73, v74
	v_max3_f32 v184, v184, v91, v92
	v_max3_f32 v202, v202, v75, v76
	v_max_f32_e32 v203, v79, v79
	v_max_f32_e32 v204, v95, v95
	v_max3_f32 v184, v184, v93, v94
	v_max3_f32 v202, v202, v77, v78
	v_max_f32_e32 v203, v204, v203
	v_max3_f32 v184, v184, v202, v203
	v_mov_b32_e32 v202, v184
	s_nop 1
	v_permlane32_swap_b32_e32 v202, v184
	v_max_f32_e32 v184, v184, v202
	v_cmp_lt_f32_e32 vcc, s87, v184
	s_cbranch_vccz .LBB0_233
	v_max_f32_e32 v184, v184, v184
	v_max_f32_e32 v184, 0, v184
	v_exp_f32_e64 v202, -v184
	v_add_f32_e32 v226, v226, v184
	v_pk_add_f32 v[80:81], v[80:81], v[184:185] op_sel_hi:[1,0] neg_lo:[0,1] neg_hi:[0,1]
	v_mul_f32_e32 v222, v222, v202
	v_pk_mul_f32 v[62:63], v[62:63], v[202:203] op_sel_hi:[1,0]
	v_pk_mul_f32 v[60:61], v[60:61], v[202:203] op_sel_hi:[1,0]
	v_pk_mul_f32 v[58:59], v[58:59], v[202:203] op_sel_hi:[1,0]
	v_pk_mul_f32 v[56:57], v[56:57], v[202:203] op_sel_hi:[1,0]
	v_pk_mul_f32 v[54:55], v[54:55], v[202:203] op_sel_hi:[1,0]
	v_pk_mul_f32 v[52:53], v[52:53], v[202:203] op_sel_hi:[1,0]
	v_pk_mul_f32 v[50:51], v[50:51], v[202:203] op_sel_hi:[1,0]
	v_pk_mul_f32 v[48:49], v[48:49], v[202:203] op_sel_hi:[1,0]
	v_pk_mul_f32 v[46:47], v[46:47], v[202:203] op_sel_hi:[1,0]
	v_pk_mul_f32 v[44:45], v[44:45], v[202:203] op_sel_hi:[1,0]
	v_pk_mul_f32 v[42:43], v[42:43], v[202:203] op_sel_hi:[1,0]
	v_pk_mul_f32 v[40:41], v[40:41], v[202:203] op_sel_hi:[1,0]
	v_pk_mul_f32 v[38:39], v[38:39], v[202:203] op_sel_hi:[1,0]
	v_pk_mul_f32 v[36:37], v[36:37], v[202:203] op_sel_hi:[1,0]
	v_pk_mul_f32 v[34:35], v[34:35], v[202:203] op_sel_hi:[1,0]
	v_pk_mul_f32 v[32:33], v[32:33], v[202:203] op_sel_hi:[1,0]
	v_pk_mul_f32 v[30:31], v[30:31], v[202:203] op_sel_hi:[1,0]
	v_pk_mul_f32 v[28:29], v[28:29], v[202:203] op_sel_hi:[1,0]
	v_pk_mul_f32 v[26:27], v[26:27], v[202:203] op_sel_hi:[1,0]
	v_pk_mul_f32 v[24:25], v[24:25], v[202:203] op_sel_hi:[1,0]
	v_pk_mul_f32 v[22:23], v[22:23], v[202:203] op_sel_hi:[1,0]
	v_pk_mul_f32 v[20:21], v[20:21], v[202:203] op_sel_hi:[1,0]
	v_pk_mul_f32 v[18:19], v[18:19], v[202:203] op_sel_hi:[1,0]
	v_pk_mul_f32 v[16:17], v[16:17], v[202:203] op_sel_hi:[1,0]
	v_pk_mul_f32 v[14:15], v[14:15], v[202:203] op_sel_hi:[1,0]
	v_pk_mul_f32 v[12:13], v[12:13], v[202:203] op_sel_hi:[1,0]
	v_pk_mul_f32 v[10:11], v[10:11], v[202:203] op_sel_hi:[1,0]
	v_pk_mul_f32 v[8:9], v[8:9], v[202:203] op_sel_hi:[1,0]
	v_pk_mul_f32 v[6:7], v[6:7], v[202:203] op_sel_hi:[1,0]
	v_pk_mul_f32 v[4:5], v[4:5], v[202:203] op_sel_hi:[1,0]
	v_pk_mul_f32 v[2:3], v[2:3], v[202:203] op_sel_hi:[1,0]
	v_pk_mul_f32 v[0:1], v[0:1], v[202:203] op_sel_hi:[1,0]
	v_pk_add_f32 v[64:65], v[64:65], v[184:185] op_sel_hi:[1,0] neg_lo:[0,1] neg_hi:[0,1]
	v_pk_add_f32 v[82:83], v[82:83], v[184:185] op_sel_hi:[1,0] neg_lo:[0,1] neg_hi:[0,1]
	v_pk_add_f32 v[66:67], v[66:67], v[184:185] op_sel_hi:[1,0] neg_lo:[0,1] neg_hi:[0,1]
	v_pk_add_f32 v[84:85], v[84:85], v[184:185] op_sel_hi:[1,0] neg_lo:[0,1] neg_hi:[0,1]
	v_pk_add_f32 v[68:69], v[68:69], v[184:185] op_sel_hi:[1,0] neg_lo:[0,1] neg_hi:[0,1]
	v_pk_add_f32 v[86:87], v[86:87], v[184:185] op_sel_hi:[1,0] neg_lo:[0,1] neg_hi:[0,1]
	v_pk_add_f32 v[70:71], v[70:71], v[184:185] op_sel_hi:[1,0] neg_lo:[0,1] neg_hi:[0,1]
	v_pk_add_f32 v[88:89], v[88:89], v[184:185] op_sel_hi:[1,0] neg_lo:[0,1] neg_hi:[0,1]
	v_pk_add_f32 v[72:73], v[72:73], v[184:185] op_sel_hi:[1,0] neg_lo:[0,1] neg_hi:[0,1]
	v_pk_add_f32 v[90:91], v[90:91], v[184:185] op_sel_hi:[1,0] neg_lo:[0,1] neg_hi:[0,1]
	v_pk_add_f32 v[74:75], v[74:75], v[184:185] op_sel_hi:[1,0] neg_lo:[0,1] neg_hi:[0,1]
	v_pk_add_f32 v[92:93], v[92:93], v[184:185] op_sel_hi:[1,0] neg_lo:[0,1] neg_hi:[0,1]
	v_pk_add_f32 v[76:77], v[76:77], v[184:185] op_sel_hi:[1,0] neg_lo:[0,1] neg_hi:[0,1]
	v_pk_add_f32 v[94:95], v[94:95], v[184:185] op_sel_hi:[1,0] neg_lo:[0,1] neg_hi:[0,1]
	v_pk_add_f32 v[78:79], v[78:79], v[184:185] op_sel_hi:[1,0] neg_lo:[0,1] neg_hi:[0,1]

; template <bool SWAP, bool SSQ, class AF>
; DI void gemm_main(AF asrc, int m0, const u16* __restrict__ Bw, int ldb, int K, char* smem,
;                   f32x16 (&acc)[4][2], float ssq_eps, float (&rs)[4]) {
;     ...
;   auto gload = [&](int kt) {
;     ASrc s = asrc(kt);
;     const unsigned voffA = (unsigned)(srow * (int)s.ld * 2 + skc * 16);
;     const char* ua = (const char*)s.p + (long)m0 * s.ld * 2;
; #pragma unroll
;     for (int i = 0; i < 8; ++i) ra[i] = *(const u32x4*)(ua + (long)(32 * i) * s.ld * 2 + voffA);
;     const char* ub = (const char*)Bw + (long)kt * 128;
; #pragma unroll
;     for (int i = 0; i < 4; ++i) rb[i] = *(const u32x4*)(ub + (long)(32 * i) * ldb * 2 + voffB);
;   };
;   auto sstore = [&]() {
; #pragma unroll
;     for (int i = 0; i < 8; ++i) *(u32x4*)(sA + lds_st + i * (32 * 144)) = ra[i];
; #pragma unroll
;     for (int i = 0; i < 4; ++i) *(u32x4*)(sB + lds_st + i * (32 * 144)) = rb[i];
;   };
;   const int nkt = K >> 6;
;   const char* pA = sA + (wm * 128 + lr) * 144 + lh * 16;
;   const char* pB = sB + (wn * 64 + lr) * 144 + lh * 16;
;   gload(0);
;   sstore();
;   __syncthreads();
; DI void phase_inproj(const Params& p, const GroupP& g, int l, char* smem, int vb) {
;     ...
;   for (int it = vb; it < ((ntiles + 7) & ~7); it += gridDim.x) {
;     const int tt = xcd_tile(it, ntiles);
;     if (tt < 0) continue;
;     int nt, mt;
;     tile_mn(tt, nmt, 43, mt, nt);
;     int m0 = mt * 256, n0 = nt * 128;
;     f32x16 acc[4][2];
;     const u16* xb = (l == 0) ? g.xb : g.h1b;
;     float rsd[4];
;     gemm_main<true, false>([&](int kt) { return ASrc{xb + kt * 64, DM}; }, m0, W + (long)n0 * DM, DM, DM, smem, acc, 0.f, rsd);
.LBB0_453:
	s_cmp_lt_i32 s8, 0
	s_cbranch_scc1 .LBB0_450
	s_mul_hi_u32 s9, s8, 0x2fa0be83
	s_lshr_b32 s9, s9, 5
	s_mul_i32 s10, s9, 0xffffff54
	s_lshl_b32 s9, s9, 2
	s_add_i32 s8, s10, s8
	s_sub_i32 s10, s53, s9
	s_min_i32 s10, s10, 4
	s_abs_i32 s13, s10
	v_cvt_f32_u32_e32 v0, s13
	s_sub_i32 s14, 0, s13
	s_abs_i32 s12, s8
	s_xor_b32 s11, s8, s10
	v_rcp_iflag_f32_e32 v0, v0
	s_ashr_i32 s11, s11, 31
	v_mov_b32_e32 v1, v200
	v_mul_f32_e32 v0, 0x4f7ffffe, v0
	v_cvt_u32_f32_e32 v0, v0
	v_ashrrev_i32_e32 v2, 3, v1
	s_movk_i32 s16, 0x90
	v_and_b32_e32 v3, 31, v1
	v_readfirstlane_b32 s15, v0
	s_mul_i32 s14, s14, s15
	s_mul_hi_u32 s14, s15, s14
	s_add_i32 s15, s15, s14
	s_mul_hi_u32 s14, s12, s15
	s_mul_i32 s15, s14, s13
	s_sub_i32 s12, s12, s15
	s_add_i32 s15, s14, 1
	s_sub_i32 s34, s12, s13
	s_cmp_ge_u32 s12, s13
	s_cselect_b32 s14, s15, s14
	s_cselect_b32 s12, s34, s12
	s_add_i32 s15, s14, 1
	s_cmp_ge_u32 s12, s13
	s_cselect_b32 s12, s15, s14
	s_xor_b32 s12, s12, s11
	s_sub_i32 s11, s12, s11
	s_mul_i32 s10, s11, s10
	s_add_i32 s8, s8, s9
	s_sub_i32 s8, s8, s10
	s_lshl_b32 s10, s8, 8
	s_lshl_b32 s8, s11, 7
	s_ashr_i32 s9, s8, 31
	s_lshl_b64 s[12:13], s[8:9], 12
	s_add_u32 s14, s33, s12
	v_readfirstlane_b32 s9, v1
	v_lshlrev_b32_e32 v0, 4, v1
	s_addc_u32 s15, s85, s13
	v_and_b32_e32 v0, 0x70, v0
	s_and_b32 s11, s9, 0xfffff80
	v_mad_u64_u32 v[136:137], s[34:35], v2, s16, v[0:1]
	v_lshl_or_b32 v184, v2, 12, v0
	v_or_b32_e32 v0, s11, v3
	s_ashr_i32 s11, s10, 31
	s_lshl_b64 s[34:35], s[10:11], 12
	s_add_u32 s34, s59, s34
	s_addc_u32 s35, s58, s35
	v_lshl_add_u64 v[138:139], s[34:35], 0, v[184:185]
	v_mul_lo_u32 v48, v0, s16
	v_lshrrev_b32_e32 v0, 1, v1
	v_add_co_u32_e32 v4, vcc, s75, v138
	v_and_b32_e32 v49, 16, v0
	v_and_or_b32 v0, s9, 64, v3
	v_addc_co_u32_e32 v5, vcc, 0, v139, vcc
	s_mov_b32 s9, 0x40000
	v_add_co_u32_e32 v8, vcc, s9, v138
	v_mul_u32_u24_e32 v50, 0x90, v0
	global_load_dwordx4 v[0:3], v184, s[34:35]
	v_addc_co_u32_e32 v9, vcc, 0, v139, vcc
	s_mov_b32 s34, 0x60000
	v_add_co_u32_e32 v12, vcc, s34, v138
	s_mov_b32 s35, 0x80000
	s_nop 0
	v_addc_co_u32_e32 v13, vcc, 0, v139, vcc
	v_add_co_u32_e32 v16, vcc, s35, v138
	s_mov_b32 s36, 0xa0000
	s_nop 0
	v_addc_co_u32_e32 v17, vcc, 0, v139, vcc
	v_add_co_u32_e32 v20, vcc, s36, v138
	s_mov_b32 s37, 0xc0000
	s_nop 0
	v_addc_co_u32_e32 v21, vcc, 0, v139, vcc
	global_load_dwordx4 v[4:7], v[4:5], off
	v_add_co_u32_e32 v24, vcc, s37, v138
	global_load_dwordx4 v[8:11], v[8:9], off
	s_nop 0
	v_addc_co_u32_e32 v25, vcc, 0, v139, vcc
	s_mov_b32 s38, 0xe0000
	global_load_dwordx4 v[12:15], v[12:13], off
	v_add_co_u32_e32 v28, vcc, s38, v138
	global_load_dwordx4 v[16:19], v[16:17], off
	s_nop 0
	v_addc_co_u32_e32 v29, vcc, 0, v139, vcc
	v_lshl_add_u64 v[44:45], s[14:15], 0, v[184:185]
	global_load_dwordx4 v[20:23], v[20:21], off
	v_add_co_u32_e32 v36, vcc, s75, v44
	global_load_dwordx4 v[24:27], v[24:25], off
	s_nop 0
	v_addc_co_u32_e32 v37, vcc, 0, v45, vcc
	global_load_dwordx4 v[28:31], v[28:29], off
	v_add_co_u32_e32 v40, vcc, s9, v44
	global_load_dwordx4 v[32:35], v184, s[14:15]
	s_nop 0
	v_addc_co_u32_e32 v41, vcc, 0, v45, vcc
	global_load_dwordx4 v[36:39], v[36:37], off
	v_add_co_u32_e32 v44, vcc, s34, v44
	global_load_dwordx4 v[40:43], v[40:41], off
	s_nop 0
	v_addc_co_u32_e32 v45, vcc, 0, v45, vcc
	global_load_dwordx4 v[44:47], v[44:45], off
	s_add_u32 s12, s4, s12
	s_addc_u32 s13, s63, s13
	v_lshl_add_u64 v[140:141], s[12:13], 0, v[184:185]
	s_mov_b64 s[12:13], 0
	v_add_u32_e32 v137, v48, v49
	v_add_u32_e32 v142, v50, v49
	s_waitcnt vmcnt(11)
	ds_write_b128 v136, v[0:3]
	s_waitcnt vmcnt(10)
	ds_write_b128 v136, v[4:7] offset:4608
	s_waitcnt vmcnt(9)
	ds_write_b128 v136, v[8:11] offset:9216
	s_waitcnt vmcnt(8)
	ds_write_b128 v136, v[12:15] offset:13824
	s_waitcnt vmcnt(7)
	ds_write_b128 v136, v[16:19] offset:18432
	s_waitcnt vmcnt(6)
	ds_write_b128 v136, v[20:23] offset:23040
	s_waitcnt vmcnt(5)
	ds_write_b128 v136, v[24:27] offset:27648
	s_waitcnt vmcnt(4)
	ds_write_b128 v136, v[28:31] offset:32256
	s_waitcnt vmcnt(3)
	ds_write_b128 v136, v[32:35] offset:36864
	s_waitcnt vmcnt(2)
	ds_write_b128 v136, v[36:39] offset:41472
	s_waitcnt vmcnt(1)
	ds_write_b128 v136, v[40:43] offset:46080
	s_waitcnt vmcnt(0)
	ds_write_b128 v136, v[44:47] offset:50688
	v_mov_b32_e32 v0, 0
	v_mov_b32_e32 v1, v0
	v_mov_b32_e32 v2, v0
	v_mov_b32_e32 v3, v0
	v_mov_b32_e32 v4, v0
	v_mov_b32_e32 v5, v0
	v_mov_b32_e32 v6, v0
	v_mov_b32_e32 v7, v0
	v_mov_b32_e32 v8, v0
	v_mov_b32_e32 v9, v0
	v_mov_b32_e32 v10, v0
	v_mov_b32_e32 v11, v0
	v_mov_b32_e32 v12, v0
	v_mov_b32_e32 v13, v0
	v_mov_b32_e32 v14, v0
	v_mov_b32_e32 v15, v0
	v_mov_b32_e32 v16, v0
	v_mov_b32_e32 v17, v0
	v_mov_b32_e32 v18, v0
	v_mov_b32_e32 v19, v0
	v_mov_b32_e32 v20, v0
	v_mov_b32_e32 v21, v0
	v_mov_b32_e32 v22, v0
	v_mov_b32_e32 v23, v0
	v_mov_b32_e32 v24, v0
	v_mov_b32_e32 v25, v0
	v_mov_b32_e32 v26, v0
	v_mov_b32_e32 v27, v0
	v_mov_b32_e32 v28, v0
	v_mov_b32_e32 v29, v0
	v_mov_b32_e32 v30, v0
	v_mov_b32_e32 v31, v0
	v_mov_b32_e32 v32, v0
	v_mov_b32_e32 v33, v0
	v_mov_b32_e32 v34, v0
	v_mov_b32_e32 v35, v0
	v_mov_b32_e32 v36, v0
	v_mov_b32_e32 v37, v0
	v_mov_b32_e32 v38, v0
	v_mov_b32_e32 v39, v0
	v_mov_b32_e32 v40, v0
	v_mov_b32_e32 v41, v0
	v_mov_b32_e32 v42, v0
	v_mov_b32_e32 v43, v0
	v_mov_b32_e32 v44, v0
	v_mov_b32_e32 v45, v0
	v_mov_b32_e32 v46, v0
	v_mov_b32_e32 v47, v0
	v_mov_b32_e32 v48, v0
	v_mov_b32_e32 v49, v0
	v_mov_b32_e32 v50, v0
	v_mov_b32_e32 v51, v0
	v_mov_b32_e32 v52, v0
	v_mov_b32_e32 v53, v0
	v_mov_b32_e32 v54, v0
	v_mov_b32_e32 v55, v0
	v_mov_b32_e32 v56, v0
	v_mov_b32_e32 v57, v0
	v_mov_b32_e32 v58, v0
	v_mov_b32_e32 v59, v0
; #define MFMA(a, b, c) __builtin_amdgcn_mfma_f32_32x32x16_bf16((a), (b), (c), 0, 0, 0)
; template <bool SWAP, bool SSQ, class AF>
; DI void gemm_main(AF asrc, int m0, const u16* __restrict__ Bw, int ldb, int K, char* smem,
;                   f32x16 (&acc)[4][2], float ssq_eps, float (&rs)[4]) {
;     ...
;   gload(0);
;   sstore();
;   __syncthreads();
;   for (int kt = 0; kt < nkt; ++kt) {
;     if (kt + 1 < nkt) gload(kt + 1);
;     __builtin_amdgcn_sched_barrier(0);
;     {
;       bf16x8 ar[3], br[2][2];
;       ar[0] = *(const bf16x8*)(pA);
;       ar[1] = *(const bf16x8*)(pA + 32 * 144);
;       br[0][0] = *(const bf16x8*)(pB);
;       br[0][1] = *(const bf16x8*)(pB + 32 * 144);
;       __builtin_amdgcn_sched_group_barrier(0x100, 4, 0);
; #pragma unroll
;       for (int t = 0; t < 16; ++t) {
;         const int ks = t >> 2, mi = t & 3;
;         if (t + 2 < 16) {
;           ar[(t + 2) % 3] = *(const bf16x8*)(pA + ((t + 2) & 3) * (32 * 144) + ((t + 2) >> 2) * 32);
;           if (mi == 1 && ks + 1 < 4) {
;             br[(ks + 1) & 1][0] = *(const bf16x8*)(pB + (ks + 1) * 32);
;             br[(ks + 1) & 1][1] = *(const bf16x8*)(pB + 32 * 144 + (ks + 1) * 32);
;             __builtin_amdgcn_sched_group_barrier(0x100, 3, 0);
;           } else {
;             __builtin_amdgcn_sched_group_barrier(0x100, 1, 0);
;           }
;         }
;         acc[mi][0] = SWAP ? MFMA(br[ks & 1][0], ar[t % 3], acc[mi][0]) : MFMA(ar[t % 3], br[ks & 1][0], acc[mi][0]);
;         acc[mi][1] = SWAP ? MFMA(br[ks & 1][1], ar[t % 3], acc[mi][1]) : MFMA(ar[t % 3], br[ks & 1][1], acc[mi][1]);
;         __builtin_amdgcn_sched_group_barrier(0x008, 2, 0);
;         if (SSQ) {
;           u32x4 u = __builtin_bit_cast(u32x4, ar[t % 3]);
; #pragma unroll
;           for (int j = 0; j < 4; ++j) rs[mi] = dot2bf(u[j], rs[mi]);
;         }
;       }
	v_mov_b32_e32 v60, v0
	v_mov_b32_e32 v61, v0
	v_mov_b32_e32 v62, v0
	v_mov_b32_e32 v63, v0
	v_mov_b32_e32 v64, v0
	v_mov_b32_e32 v65, v0
	v_mov_b32_e32 v66, v0
	v_mov_b32_e32 v67, v0
	v_mov_b32_e32 v68, v0
	v_mov_b32_e32 v69, v0
	v_mov_b32_e32 v70, v0
	v_mov_b32_e32 v71, v0
	v_mov_b32_e32 v72, v0
	v_mov_b32_e32 v73, v0
	v_mov_b32_e32 v74, v0
	v_mov_b32_e32 v75, v0
	v_mov_b32_e32 v76, v0
	v_mov_b32_e32 v77, v0
	v_mov_b32_e32 v78, v0
	v_mov_b32_e32 v79, v0
	v_mov_b32_e32 v80, v0
	v_mov_b32_e32 v81, v0
	v_mov_b32_e32 v82, v0
	v_mov_b32_e32 v83, v0
	v_mov_b32_e32 v84, v0
	v_mov_b32_e32 v85, v0
	v_mov_b32_e32 v86, v0
	v_mov_b32_e32 v87, v0
	v_mov_b32_e32 v88, v0
	v_mov_b32_e32 v89, v0
	v_mov_b32_e32 v90, v0
	v_mov_b32_e32 v91, v0
	v_mov_b32_e32 v92, v0
	v_mov_b32_e32 v93, v0
	v_mov_b32_e32 v94, v0
	v_mov_b32_e32 v95, v0
	v_mov_b32_e32 v96, v0
	v_mov_b32_e32 v97, v0
	v_mov_b32_e32 v98, v0
	v_mov_b32_e32 v99, v0
	v_mov_b32_e32 v100, v0
	v_mov_b32_e32 v101, v0
	v_mov_b32_e32 v102, v0
	v_mov_b32_e32 v103, v0
	v_mov_b32_e32 v104, v0
	v_mov_b32_e32 v105, v0
	v_mov_b32_e32 v106, v0
	v_mov_b32_e32 v107, v0
	v_mov_b32_e32 v108, v0
	v_mov_b32_e32 v109, v0
	v_mov_b32_e32 v110, v0
	v_mov_b32_e32 v111, v0
	v_mov_b32_e32 v112, v0
	v_mov_b32_e32 v113, v0
	v_mov_b32_e32 v114, v0
	v_mov_b32_e32 v115, v0
	v_mov_b32_e32 v116, v0
	v_mov_b32_e32 v117, v0
	v_mov_b32_e32 v118, v0
	v_mov_b32_e32 v119, v0
	v_mov_b32_e32 v120, v0
	v_mov_b32_e32 v121, v0
	v_mov_b32_e32 v122, v0
	v_mov_b32_e32 v123, v0
	v_mov_b32_e32 v124, v0
	v_mov_b32_e32 v125, v0
	v_mov_b32_e32 v126, v0
	v_mov_b32_e32 v127, v0
	s_waitcnt lgkmcnt(0)
	s_barrier
	v_readfirstlane_b32 s9, v184
	v_readfirstlane_b32 s34, v138
	v_readfirstlane_b32 s35, v139
	v_readfirstlane_b32 s100, v140
	v_readfirstlane_b32 s101, v141
	v_subrev_u32_e32 v198, s9, v184
	s_add_u32 s34, s34, 0x80
	s_addc_u32 s35, s35, 0
	s_add_u32 s36, s34, 0x80000
	s_addc_u32 s37, s35, 0
	s_add_u32 s100, s100, 0x80
	s_addc_u32 s101, s101, 0
	v_add_u32_e32 v199, 0x20000, v198
	v_add_u32_e32 v217, 0x40000, v198
	v_add_u32_e32 v250, 0x60000, v198
	ds_read_b128 v[218:221], v142 offset:36864
	ds_read_b128 v[222:225], v142 offset:41472
	ds_read_b128 v[226:229], v137
	ds_read_b128 v[230:233], v137 offset:4608
	ds_read_b128 v[234:237], v137 offset:9216
.LBB0_455:
	ds_read_b128 v[238:241], v137 offset:13824
	global_load_dwordx4 v[144:147], v198, s[34:35]
	s_waitcnt lgkmcnt(3)
	v_mfma_f32_32x32x16_bf16 v[112:127], v[218:221], v[226:229], v[112:127]
	v_mfma_f32_32x32x16_bf16 v[96:111], v[222:225], v[226:229], v[96:111]
	ds_read_b128 v[226:229], v142 offset:36896
	ds_read_b128 v[242:245], v142 offset:41504
	global_load_dwordx4 v[150:153], v199, s[34:35]
	global_load_dwordx4 v[154:157], v217, s[34:35]
	s_waitcnt lgkmcnt(4)
	v_mfma_f32_32x32x16_bf16 v[80:95], v[218:221], v[230:233], v[80:95]
	v_mfma_f32_32x32x16_bf16 v[64:79], v[222:225], v[230:233], v[64:79]
	ds_read_b128 v[230:233], v137 offset:32
	global_load_dwordx4 v[158:161], v250, s[34:35]
	s_waitcnt lgkmcnt(4)
	v_mfma_f32_32x32x16_bf16 v[48:63], v[218:221], v[234:237], v[48:63]
	v_mfma_f32_32x32x16_bf16 v[32:47], v[222:225], v[234:237], v[32:47]
	ds_read_b128 v[234:237], v137 offset:4640
	global_load_dwordx4 v[162:165], v198, s[36:37]
	s_waitcnt lgkmcnt(4)
	v_mfma_f32_32x32x16_bf16 v[16:31], v[218:221], v[238:241], v[16:31]
	v_mfma_f32_32x32x16_bf16 v[0:15], v[222:225], v[238:241], v[0:15]
	ds_read_b128 v[218:221], v137 offset:9248
	ds_read_b128 v[222:225], v137 offset:13856
	global_load_dwordx4 v[166:169], v199, s[36:37]
	s_waitcnt lgkmcnt(3)
	v_mfma_f32_32x32x16_bf16 v[112:127], v[226:229], v[230:233], v[112:127]
	v_mfma_f32_32x32x16_bf16 v[96:111], v[242:245], v[230:233], v[96:111]
	ds_read_b128 v[230:233], v142 offset:36928
	ds_read_b128 v[202:205], v142 offset:41536
	global_load_dwordx4 v[170:173], v217, s[36:37]
	s_waitcnt lgkmcnt(4)
	v_mfma_f32_32x32x16_bf16 v[80:95], v[226:229], v[234:237], v[80:95]
	v_mfma_f32_32x32x16_bf16 v[64:79], v[242:245], v[234:237], v[64:79]
	ds_read_b128 v[234:237], v137 offset:64
	ds_read_b128 v[206:209], v137 offset:4672
	global_load_dwordx4 v[174:177], v250, s[36:37]
	s_waitcnt lgkmcnt(5)
	v_mfma_f32_32x32x16_bf16 v[48:63], v[226:229], v[218:221], v[48:63]
	v_mfma_f32_32x32x16_bf16 v[32:47], v[242:245], v[218:221], v[32:47]
	ds_read_b128 v[218:221], v137 offset:9280
	global_load_dwordx4 v[178:181], v198, s[100:101]
	s_waitcnt lgkmcnt(5)
	v_mfma_f32_32x32x16_bf16 v[16:31], v[226:229], v[222:225], v[16:31]
	v_mfma_f32_32x32x16_bf16 v[0:15], v[242:245], v[222:225], v[0:15]
	ds_read_b128 v[226:229], v137 offset:13888
	ds_read_b128 v[246:249], v142 offset:36960
	ds_read_b128 v[238:241], v142 offset:41568
	global_load_dwordx4 v[186:189], v199, s[100:101]
	s_waitcnt lgkmcnt(5)
	v_mfma_f32_32x32x16_bf16 v[112:127], v[230:233], v[234:237], v[112:127]
	v_mfma_f32_32x32x16_bf16 v[96:111], v[202:205], v[234:237], v[96:111]
	ds_read_b128 v[222:225], v137 offset:96
	ds_read_b128 v[234:237], v137 offset:4704
	global_load_dwordx4 v[190:193], v217, s[100:101]
	s_waitcnt lgkmcnt(6)
	v_mfma_f32_32x32x16_bf16 v[80:95], v[230:233], v[206:209], v[80:95]
	v_mfma_f32_32x32x16_bf16 v[64:79], v[202:205], v[206:209], v[64:79]
	ds_read_b128 v[242:245], v137 offset:9312
	ds_read_b128 v[206:209], v137 offset:13920
	global_load_dwordx4 v[194:197], v250, s[100:101]
	s_waitcnt lgkmcnt(0)
	s_barrier
; #define MFMA(a, b, c) __builtin_amdgcn_mfma_f32_32x32x16_bf16((a), (b), (c), 0, 0, 0)
; template <bool SWAP, bool SSQ, class AF>
; DI void gemm_main(AF asrc, int m0, const u16* __restrict__ Bw, int ldb, int K, char* smem,
;                   f32x16 (&acc)[4][2], float ssq_eps, float (&rs)[4]) {
;     ...
;   for (int kt = 0; kt < nkt; ++kt) {
;     if (kt + 1 < nkt) gload(kt + 1);
;     __builtin_amdgcn_sched_barrier(0);
;     {
;       bf16x8 ar[3], br[2][2];
;       ar[0] = *(const bf16x8*)(pA);
;       ar[1] = *(const bf16x8*)(pA + 32 * 144);
;       br[0][0] = *(const bf16x8*)(pB);
;       br[0][1] = *(const bf16x8*)(pB + 32 * 144);
;       __builtin_amdgcn_sched_group_barrier(0x100, 4, 0);
; #pragma unroll
;       for (int t = 0; t < 16; ++t) {
;         const int ks = t >> 2, mi = t & 3;
;         if (t + 2 < 16) {
;           ar[(t + 2) % 3] = *(const bf16x8*)(pA + ((t + 2) & 3) * (32 * 144) + ((t + 2) >> 2) * 32);
;           if (mi == 1 && ks + 1 < 4) {
;             br[(ks + 1) & 1][0] = *(const bf16x8*)(pB + (ks + 1) * 32);
;             br[(ks + 1) & 1][1] = *(const bf16x8*)(pB + 32 * 144 + (ks + 1) * 32);
;             __builtin_amdgcn_sched_group_barrier(0x100, 3, 0);
;           } else {
;             __builtin_amdgcn_sched_group_barrier(0x100, 1, 0);
;           }
;         }
;         acc[mi][0] = SWAP ? MFMA(br[ks & 1][0], ar[t % 3], acc[mi][0]) : MFMA(ar[t % 3], br[ks & 1][0], acc[mi][0]);
;         acc[mi][1] = SWAP ? MFMA(br[ks & 1][1], ar[t % 3], acc[mi][1]) : MFMA(ar[t % 3], br[ks & 1][1], acc[mi][1]);
;         __builtin_amdgcn_sched_group_barrier(0x008, 2, 0);
;         if (SSQ) {
;           u32x4 u = __builtin_bit_cast(u32x4, ar[t % 3]);
; #pragma unroll
;           for (int j = 0; j < 4; ++j) rs[mi] = dot2bf(u[j], rs[mi]);
;         }
;       }
;     }
;     __syncthreads();
;     if (kt + 1 < nkt) sstore();
;     __syncthreads();
;   }
	v_mfma_f32_32x32x16_bf16 v[48:63], v[230:233], v[218:221], v[48:63]
	v_mfma_f32_32x32x16_bf16 v[32:47], v[202:205], v[218:221], v[32:47]
	s_waitcnt vmcnt(11)
	ds_write_b128 v136, v[144:147]
	s_waitcnt vmcnt(10)
	ds_write_b128 v136, v[150:153] offset:4608
	s_waitcnt vmcnt(9)
	ds_write_b128 v136, v[154:157] offset:9216
	v_mfma_f32_32x32x16_bf16 v[16:31], v[230:233], v[226:229], v[16:31]
	v_mfma_f32_32x32x16_bf16 v[0:15], v[202:205], v[226:229], v[0:15]
	s_waitcnt vmcnt(8)
	ds_write_b128 v136, v[158:161] offset:13824
	s_waitcnt vmcnt(7)
	ds_write_b128 v136, v[162:165] offset:18432
	s_waitcnt vmcnt(6)
	ds_write_b128 v136, v[166:169] offset:23040
	v_mfma_f32_32x32x16_bf16 v[112:127], v[246:249], v[222:225], v[112:127]
	v_mfma_f32_32x32x16_bf16 v[96:111], v[238:241], v[222:225], v[96:111]
	s_waitcnt vmcnt(5)
	ds_write_b128 v136, v[170:173] offset:27648
	s_waitcnt vmcnt(4)
	ds_write_b128 v136, v[174:177] offset:32256
	s_waitcnt vmcnt(3)
	ds_write_b128 v136, v[178:181] offset:36864
	v_mfma_f32_32x32x16_bf16 v[80:95], v[246:249], v[234:237], v[80:95]
	v_mfma_f32_32x32x16_bf16 v[64:79], v[238:241], v[234:237], v[64:79]
	s_waitcnt vmcnt(2)
	ds_write_b128 v136, v[186:189] offset:41472
	s_waitcnt vmcnt(1)
	ds_write_b128 v136, v[190:193] offset:46080
	s_waitcnt vmcnt(0)
	ds_write_b128 v136, v[194:197] offset:50688
	s_waitcnt lgkmcnt(0)
	s_barrier
	ds_read_b128 v[218:221], v142 offset:36864
	ds_read_b128 v[222:225], v142 offset:41472
	ds_read_b128 v[226:229], v137
	ds_read_b128 v[230:233], v137 offset:4608
	ds_read_b128 v[234:237], v137 offset:9216
	v_mfma_f32_32x32x16_bf16 v[48:63], v[246:249], v[242:245], v[48:63]
	v_mfma_f32_32x32x16_bf16 v[32:47], v[238:241], v[242:245], v[32:47]
	v_mfma_f32_32x32x16_bf16 v[16:31], v[246:249], v[206:209], v[16:31]
	v_mfma_f32_32x32x16_bf16 v[0:15], v[238:241], v[206:209], v[0:15]
	s_add_u32 s34, s34, 0x80
	s_addc_u32 s35, s35, 0
	s_add_u32 s36, s36, 0x80
	s_addc_u32 s37, s37, 0
	s_add_u32 s100, s100, 0x80
	s_addc_u32 s101, s101, 0
	s_add_u32 s12, s12, 0x80
	s_cmpk_lg_i32 s12, 0xf80
	s_cbranch_scc1 .LBB0_455
	ds_read_b128 v[138:141], v142 offset:36864
	ds_read_b128 v[154:157], v142 offset:41472
	ds_read_b128 v[144:147], v137
	ds_read_b128 v[150:153], v137 offset:4608
	ds_read_b128 v[158:161], v137 offset:9216
	s_or_b32 s65, s8, s55
	s_cmpk_gt_i32 s65, 0x153f
	s_waitcnt lgkmcnt(2)
	v_mfma_f32_32x32x16_bf16 v[112:127], v[138:141], v[144:147], v[112:127]
	v_mfma_f32_32x32x16_bf16 v[96:111], v[154:157], v[144:147], v[96:111]
	ds_read_b128 v[162:165], v142 offset:36896
	ds_read_b128 v[166:169], v142 offset:41504
	ds_read_b128 v[144:147], v137 offset:13824
	s_waitcnt lgkmcnt(4)
	v_mfma_f32_32x32x16_bf16 v[80:95], v[138:141], v[150:153], v[80:95]
	v_mfma_f32_32x32x16_bf16 v[64:79], v[154:157], v[150:153], v[64:79]
	ds_read_b128 v[150:153], v137 offset:32
	s_waitcnt lgkmcnt(4)
	v_mfma_f32_32x32x16_bf16 v[48:63], v[138:141], v[158:161], v[48:63]
	v_mfma_f32_32x32x16_bf16 v[32:47], v[154:157], v[158:161], v[32:47]
	ds_read_b128 v[158:161], v137 offset:4640
	s_waitcnt lgkmcnt(2)
	v_mfma_f32_32x32x16_bf16 v[16:31], v[138:141], v[144:147], v[16:31]
	v_mfma_f32_32x32x16_bf16 v[0:15], v[154:157], v[144:147], v[0:15]
	ds_read_b128 v[138:141], v137 offset:9248
	s_waitcnt lgkmcnt(2)
	v_mfma_f32_32x32x16_bf16 v[112:127], v[162:165], v[150:153], v[112:127]
	v_mfma_f32_32x32x16_bf16 v[96:111], v[166:169], v[150:153], v[96:111]
	ds_read_b128 v[150:153], v142 offset:36928
	ds_read_b128 v[154:157], v142 offset:41536
	ds_read_b128 v[144:147], v137 offset:13856
	s_waitcnt lgkmcnt(4)
	v_mfma_f32_32x32x16_bf16 v[80:95], v[162:165], v[158:161], v[80:95]
	v_mfma_f32_32x32x16_bf16 v[64:79], v[166:169], v[158:161], v[64:79]
	ds_read_b128 v[158:161], v137 offset:64
	s_waitcnt lgkmcnt(4)
	v_mfma_f32_32x32x16_bf16 v[48:63], v[162:165], v[138:141], v[48:63]
	v_mfma_f32_32x32x16_bf16 v[32:47], v[166:169], v[138:141], v[32:47]
	ds_read_b128 v[138:141], v137 offset:4672
	s_waitcnt lgkmcnt(2)
	v_mfma_f32_32x32x16_bf16 v[16:31], v[162:165], v[144:147], v[16:31]
	v_mfma_f32_32x32x16_bf16 v[0:15], v[166:169], v[144:147], v[0:15]
	ds_read_b128 v[144:147], v137 offset:9280
	s_waitcnt lgkmcnt(2)
	v_mfma_f32_32x32x16_bf16 v[112:127], v[150:153], v[158:161], v[112:127]
	v_mfma_f32_32x32x16_bf16 v[96:111], v[154:157], v[158:161], v[96:111]
	ds_read_b128 v[162:165], v142 offset:36960
	ds_read_b128 v[166:169], v142 offset:41568
	ds_read_b128 v[158:161], v137 offset:13888
	s_waitcnt lgkmcnt(4)
	v_mfma_f32_32x32x16_bf16 v[80:95], v[150:153], v[138:141], v[80:95]
	v_mfma_f32_32x32x16_bf16 v[64:79], v[154:157], v[138:141], v[64:79]
	ds_read_b128 v[138:141], v137 offset:96
	s_waitcnt lgkmcnt(4)
	v_mfma_f32_32x32x16_bf16 v[48:63], v[150:153], v[144:147], v[48:63]
	v_mfma_f32_32x32x16_bf16 v[32:47], v[154:157], v[144:147], v[32:47]
	ds_read_b128 v[142:145], v137 offset:4704
	s_waitcnt lgkmcnt(2)
	v_mfma_f32_32x32x16_bf16 v[16:31], v[150:153], v[158:161], v[16:31]
	v_mfma_f32_32x32x16_bf16 v[0:15], v[154:157], v[158:161], v[0:15]
	ds_read_b128 v[150:153], v137 offset:9312
	s_waitcnt lgkmcnt(2)
	v_mfma_f32_32x32x16_bf16 v[112:127], v[162:165], v[138:141], v[112:127]
	v_mfma_f32_32x32x16_bf16 v[96:111], v[166:169], v[138:141], v[96:111]
	ds_read_b128 v[136:139], v137 offset:13920
	s_waitcnt lgkmcnt(0)
	s_barrier
; DI void phase_inproj(const Params& p, const GroupP& g, int l, char* smem, int vb) {
;     ...
;     const int nw0 = n0 + wn * 64;
;     if (nw0 >= INW) continue;
;     if (l == 1) {
;       const float* sq = p.rowsq + (size_t)4 * 50432 + g.seq0 + m0 + wm * 128 + lr;
; #pragma unroll
;       for (int mi = 0; mi < 4; ++mi) {
;         const float r = __builtin_amdgcn_rsqf(sq[mi * 32] * (1.f / DM) + 1e-6f);
; #pragma unroll
;         for (int ni = 0; ni < 2; ++ni)
; #pragma unroll
;           for (int i = 0; i < 16; ++i) acc[mi][ni][i] *= r;
;       }
;     }
	s_barrier
	v_mfma_f32_32x32x16_bf16 v[80:95], v[162:165], v[142:145], v[80:95]
	v_mfma_f32_32x32x16_bf16 v[64:79], v[166:169], v[142:145], v[64:79]
	v_mfma_f32_32x32x16_bf16 v[48:63], v[162:165], v[150:153], v[48:63]
	v_mfma_f32_32x32x16_bf16 v[32:47], v[166:169], v[150:153], v[32:47]
	v_mfma_f32_32x32x16_bf16 v[16:31], v[162:165], v[136:139], v[16:31]
	v_mfma_f32_32x32x16_bf16 v[0:15], v[166:169], v[136:139], v[0:15]
	s_cbranch_scc1 .LBB0_450
	v_readlane_b32 s12, v254, 31
	v_readlane_b32 s13, v254, 32
	s_andn2_b64 vcc, exec, s[12:13]
	s_cbranch_vccnz .LBB0_459
	v_lshl_add_u64 v[136:137], s[10:11], 2, v[132:133]
	global_load_dword v138, v[136:137], off
	s_waitcnt vmcnt(0)
	v_fmamk_f32 v138, v138, 0x3a000000, v215
	v_rsq_f32_e32 v138, v138
	s_nop 0
	v_pk_mul_f32 v[126:127], v[126:127], v[138:139] op_sel_hi:[1,0]
	v_pk_mul_f32 v[124:125], v[124:125], v[138:139] op_sel_hi:[1,0]
	v_pk_mul_f32 v[122:123], v[122:123], v[138:139] op_sel_hi:[1,0]
	v_pk_mul_f32 v[120:121], v[120:121], v[138:139] op_sel_hi:[1,0]
	v_pk_mul_f32 v[118:119], v[118:119], v[138:139] op_sel_hi:[1,0]
	v_pk_mul_f32 v[116:117], v[116:117], v[138:139] op_sel_hi:[1,0]
	v_pk_mul_f32 v[114:115], v[114:115], v[138:139] op_sel_hi:[1,0]
	v_pk_mul_f32 v[112:113], v[112:113], v[138:139] op_sel_hi:[1,0]
	v_pk_mul_f32 v[110:111], v[110:111], v[138:139] op_sel_hi:[1,0]
	v_pk_mul_f32 v[108:109], v[108:109], v[138:139] op_sel_hi:[1,0]
	v_pk_mul_f32 v[106:107], v[106:107], v[138:139] op_sel_hi:[1,0]
	v_pk_mul_f32 v[104:105], v[104:105], v[138:139] op_sel_hi:[1,0]
	v_pk_mul_f32 v[102:103], v[102:103], v[138:139] op_sel_hi:[1,0]
	v_pk_mul_f32 v[100:101], v[100:101], v[138:139] op_sel_hi:[1,0]
	v_pk_mul_f32 v[98:99], v[98:99], v[138:139] op_sel_hi:[1,0]
	v_pk_mul_f32 v[96:97], v[96:97], v[138:139] op_sel_hi:[1,0]
	global_load_dword v138, v[136:137], off offset:128
	s_waitcnt vmcnt(0)
	v_fmamk_f32 v138, v138, 0x3a000000, v215
	v_rsq_f32_e32 v138, v138
	s_nop 0
	v_pk_mul_f32 v[94:95], v[94:95], v[138:139] op_sel_hi:[1,0]
	v_pk_mul_f32 v[92:93], v[92:93], v[138:139] op_sel_hi:[1,0]
	v_pk_mul_f32 v[90:91], v[90:91], v[138:139] op_sel_hi:[1,0]
	v_pk_mul_f32 v[88:89], v[88:89], v[138:139] op_sel_hi:[1,0]
	v_pk_mul_f32 v[86:87], v[86:87], v[138:139] op_sel_hi:[1,0]
	v_pk_mul_f32 v[84:85], v[84:85], v[138:139] op_sel_hi:[1,0]
	v_pk_mul_f32 v[82:83], v[82:83], v[138:139] op_sel_hi:[1,0]
	v_pk_mul_f32 v[80:81], v[80:81], v[138:139] op_sel_hi:[1,0]
	v_pk_mul_f32 v[78:79], v[78:79], v[138:139] op_sel_hi:[1,0]
	v_pk_mul_f32 v[76:77], v[76:77], v[138:139] op_sel_hi:[1,0]
	v_pk_mul_f32 v[74:75], v[74:75], v[138:139] op_sel_hi:[1,0]
	v_pk_mul_f32 v[72:73], v[72:73], v[138:139] op_sel_hi:[1,0]
	v_pk_mul_f32 v[70:71], v[70:71], v[138:139] op_sel_hi:[1,0]
	v_pk_mul_f32 v[68:69], v[68:69], v[138:139] op_sel_hi:[1,0]
	v_pk_mul_f32 v[66:67], v[66:67], v[138:139] op_sel_hi:[1,0]
	v_pk_mul_f32 v[64:65], v[64:65], v[138:139] op_sel_hi:[1,0]
	global_load_dword v138, v[136:137], off offset:256
	s_waitcnt vmcnt(0)
	v_fmamk_f32 v138, v138, 0x3a000000, v215
	global_load_dword v136, v[136:137], off offset:384
	v_rsq_f32_e32 v138, v138
	s_waitcnt vmcnt(0)
	v_fmamk_f32 v136, v136, 0x3a000000, v215
	v_rsq_f32_e32 v136, v136
	v_pk_mul_f32 v[62:63], v[62:63], v[138:139] op_sel_hi:[1,0]
	v_pk_mul_f32 v[60:61], v[60:61], v[138:139] op_sel_hi:[1,0]
	v_pk_mul_f32 v[58:59], v[58:59], v[138:139] op_sel_hi:[1,0]
	v_pk_mul_f32 v[56:57], v[56:57], v[138:139] op_sel_hi:[1,0]
	v_pk_mul_f32 v[54:55], v[54:55], v[138:139] op_sel_hi:[1,0]
	v_pk_mul_f32 v[52:53], v[52:53], v[138:139] op_sel_hi:[1,0]
	v_pk_mul_f32 v[50:51], v[50:51], v[138:139] op_sel_hi:[1,0]
	v_pk_mul_f32 v[48:49], v[48:49], v[138:139] op_sel_hi:[1,0]
	v_pk_mul_f32 v[46:47], v[46:47], v[138:139] op_sel_hi:[1,0]
	v_pk_mul_f32 v[44:45], v[44:45], v[138:139] op_sel_hi:[1,0]
	v_pk_mul_f32 v[42:43], v[42:43], v[138:139] op_sel_hi:[1,0]
	v_pk_mul_f32 v[40:41], v[40:41], v[138:139] op_sel_hi:[1,0]
	v_pk_mul_f32 v[38:39], v[38:39], v[138:139] op_sel_hi:[1,0]
	v_pk_mul_f32 v[36:37], v[36:37], v[138:139] op_sel_hi:[1,0]
	v_pk_mul_f32 v[34:35], v[34:35], v[138:139] op_sel_hi:[1,0]
	v_pk_mul_f32 v[32:33], v[32:33], v[138:139] op_sel_hi:[1,0]
	v_pk_mul_f32 v[30:31], v[30:31], v[136:137] op_sel_hi:[1,0]
	v_pk_mul_f32 v[28:29], v[28:29], v[136:137] op_sel_hi:[1,0]
	v_pk_mul_f32 v[26:27], v[26:27], v[136:137] op_sel_hi:[1,0]
	v_pk_mul_f32 v[24:25], v[24:25], v[136:137] op_sel_hi:[1,0]
	v_pk_mul_f32 v[22:23], v[22:23], v[136:137] op_sel_hi:[1,0]
	v_pk_mul_f32 v[20:21], v[20:21], v[136:137] op_sel_hi:[1,0]
	v_pk_mul_f32 v[18:19], v[18:19], v[136:137] op_sel_hi:[1,0]
	v_pk_mul_f32 v[16:17], v[16:17], v[136:137] op_sel_hi:[1,0]
	v_pk_mul_f32 v[14:15], v[14:15], v[136:137] op_sel_hi:[1,0]
	v_pk_mul_f32 v[12:13], v[12:13], v[136:137] op_sel_hi:[1,0]
	v_pk_mul_f32 v[10:11], v[10:11], v[136:137] op_sel_hi:[1,0]
	v_pk_mul_f32 v[8:9], v[8:9], v[136:137] op_sel_hi:[1,0]
	v_pk_mul_f32 v[6:7], v[6:7], v[136:137] op_sel_hi:[1,0]
	v_pk_mul_f32 v[4:5], v[4:5], v[136:137] op_sel_hi:[1,0]
	v_pk_mul_f32 v[2:3], v[2:3], v[136:137] op_sel_hi:[1,0]
	v_pk_mul_f32 v[0:1], v[0:1], v[136:137] op_sel_hi:[1,0]

; template <bool SWAP, bool SSQ, class AF>
; DI void gemm_main(AF asrc, int m0, const u16* __restrict__ Bw, int ldb, int K, char* smem,
;                   f32x16 (&acc)[4][2], float ssq_eps, float (&rs)[4]) {
;     ...
;   auto gload = [&](int kt) {
;     ASrc s = asrc(kt);
;     const unsigned voffA = (unsigned)(srow * (int)s.ld * 2 + skc * 16);
;     const char* ua = (const char*)s.p + (long)m0 * s.ld * 2;
; #pragma unroll
;     for (int i = 0; i < 8; ++i) ra[i] = *(const u32x4*)(ua + (long)(32 * i) * s.ld * 2 + voffA);
;     const char* ub = (const char*)Bw + (long)kt * 128;
; #pragma unroll
;     for (int i = 0; i < 4; ++i) rb[i] = *(const u32x4*)(ub + (long)(32 * i) * ldb * 2 + voffB);
;   };
;   auto sstore = [&]() {
; #pragma unroll
;     for (int i = 0; i < 8; ++i) *(u32x4*)(sA + lds_st + i * (32 * 144)) = ra[i];
; #pragma unroll
;     for (int i = 0; i < 4; ++i) *(u32x4*)(sB + lds_st + i * (32 * 144)) = rb[i];
;   };
;   const int nkt = K >> 6;
;   const char* pA = sA + (wm * 128 + lr) * 144 + lh * 16;
;   const char* pB = sB + (wn * 64 + lr) * 144 + lh * 16;
;   gload(0);
;   sstore();
;   __syncthreads();
.LBB0_586:
	s_cmp_lt_i32 s8, 0
	s_cbranch_scc1 .LBB0_583
	s_mul_hi_u32 s9, s8, 0x2fa0be83
	s_lshr_b32 s9, s9, 5
	s_mul_i32 s10, s9, 0xffffff54
	s_lshl_b32 s9, s9, 2
	s_add_i32 s8, s10, s8
	s_sub_i32 s10, s53, s9
	s_min_i32 s10, s10, 4
	s_abs_i32 s13, s10
	v_cvt_f32_u32_e32 v0, s13
	s_sub_i32 s14, 0, s13
	s_abs_i32 s12, s8
	s_xor_b32 s11, s8, s10
	v_rcp_iflag_f32_e32 v0, v0
	s_ashr_i32 s11, s11, 31
	v_mov_b32_e32 v1, v200
	v_mul_f32_e32 v0, 0x4f7ffffe, v0
	v_cvt_u32_f32_e32 v0, v0
	v_ashrrev_i32_e32 v2, 3, v1
	s_movk_i32 s16, 0x90
	v_and_b32_e32 v3, 31, v1
	v_readfirstlane_b32 s15, v0
	s_mul_i32 s14, s14, s15
	s_mul_hi_u32 s14, s15, s14
	s_add_i32 s15, s15, s14
	s_mul_hi_u32 s14, s12, s15
	s_mul_i32 s15, s14, s13
	s_sub_i32 s12, s12, s15
	s_add_i32 s15, s14, 1
	s_sub_i32 s34, s12, s13
	s_cmp_ge_u32 s12, s13
	s_cselect_b32 s14, s15, s14
	s_cselect_b32 s12, s34, s12
	s_add_i32 s15, s14, 1
	s_cmp_ge_u32 s12, s13
	s_cselect_b32 s12, s15, s14
	s_xor_b32 s12, s12, s11
	s_sub_i32 s11, s12, s11
	s_mul_i32 s10, s11, s10
	s_add_i32 s8, s8, s9
	s_sub_i32 s8, s8, s10
	s_lshl_b32 s10, s8, 8
	s_lshl_b32 s8, s11, 7
	s_ashr_i32 s9, s8, 31
	s_lshl_b64 s[12:13], s[8:9], 12
	s_add_u32 s14, s33, s12
	v_readfirstlane_b32 s9, v1
	v_lshlrev_b32_e32 v0, 4, v1
	s_addc_u32 s15, s85, s13
	v_and_b32_e32 v0, 0x70, v0
	s_and_b32 s11, s9, 0xfffff80
	v_mad_u64_u32 v[136:137], s[34:35], v2, s16, v[0:1]
	v_lshl_or_b32 v184, v2, 12, v0
	v_or_b32_e32 v0, s11, v3
	s_ashr_i32 s11, s10, 31
	s_lshl_b64 s[34:35], s[10:11], 12
	s_add_u32 s34, s60, s34
	s_addc_u32 s35, s59, s35
	v_lshl_add_u64 v[138:139], s[34:35], 0, v[184:185]
	v_mul_lo_u32 v48, v0, s16
	v_lshrrev_b32_e32 v0, 1, v1
	v_add_co_u32_e32 v4, vcc, s75, v138
	v_and_b32_e32 v49, 16, v0
	v_and_or_b32 v0, s9, 64, v3
	v_addc_co_u32_e32 v5, vcc, 0, v139, vcc
	s_mov_b32 s9, 0x40000
	v_add_co_u32_e32 v8, vcc, s9, v138
	v_mul_u32_u24_e32 v50, 0x90, v0
	global_load_dwordx4 v[0:3], v184, s[34:35]
	v_addc_co_u32_e32 v9, vcc, 0, v139, vcc
	s_mov_b32 s34, 0x60000
	v_add_co_u32_e32 v12, vcc, s34, v138
	s_mov_b32 s35, 0x80000
	s_nop 0
	v_addc_co_u32_e32 v13, vcc, 0, v139, vcc
	v_add_co_u32_e32 v16, vcc, s35, v138
	s_mov_b32 s36, 0xa0000
	s_nop 0
	v_addc_co_u32_e32 v17, vcc, 0, v139, vcc
	v_add_co_u32_e32 v20, vcc, s36, v138
	s_mov_b32 s37, 0xc0000
	s_nop 0
	v_addc_co_u32_e32 v21, vcc, 0, v139, vcc
	global_load_dwordx4 v[4:7], v[4:5], off
	v_add_co_u32_e32 v24, vcc, s37, v138
	global_load_dwordx4 v[8:11], v[8:9], off
	s_nop 0
	v_addc_co_u32_e32 v25, vcc, 0, v139, vcc
	s_mov_b32 s38, 0xe0000
	global_load_dwordx4 v[12:15], v[12:13], off
	v_add_co_u32_e32 v28, vcc, s38, v138
	global_load_dwordx4 v[16:19], v[16:17], off
	s_nop 0
	v_addc_co_u32_e32 v29, vcc, 0, v139, vcc
	v_lshl_add_u64 v[44:45], s[14:15], 0, v[184:185]
	global_load_dwordx4 v[20:23], v[20:21], off
	v_add_co_u32_e32 v36, vcc, s75, v44
	global_load_dwordx4 v[24:27], v[24:25], off
	s_nop 0
	v_addc_co_u32_e32 v37, vcc, 0, v45, vcc
	global_load_dwordx4 v[28:31], v[28:29], off
	v_add_co_u32_e32 v40, vcc, s9, v44
	global_load_dwordx4 v[32:35], v184, s[14:15]
	s_nop 0
	v_addc_co_u32_e32 v41, vcc, 0, v45, vcc
	global_load_dwordx4 v[36:39], v[36:37], off
	v_add_co_u32_e32 v44, vcc, s34, v44
	global_load_dwordx4 v[40:43], v[40:41], off
	s_nop 0
	v_addc_co_u32_e32 v45, vcc, 0, v45, vcc
	global_load_dwordx4 v[44:47], v[44:45], off
	s_add_u32 s12, s4, s12
	s_addc_u32 s13, s51, s13
	v_lshl_add_u64 v[140:141], s[12:13], 0, v[184:185]
	s_mov_b64 s[12:13], 0
	v_add_u32_e32 v137, v48, v49
	v_add_u32_e32 v142, v50, v49
	s_waitcnt vmcnt(11)
	ds_write_b128 v136, v[0:3]
	s_waitcnt vmcnt(10)
	ds_write_b128 v136, v[4:7] offset:4608
	s_waitcnt vmcnt(9)
	ds_write_b128 v136, v[8:11] offset:9216
	s_waitcnt vmcnt(8)
	ds_write_b128 v136, v[12:15] offset:13824
	s_waitcnt vmcnt(7)
	ds_write_b128 v136, v[16:19] offset:18432
	s_waitcnt vmcnt(6)
	ds_write_b128 v136, v[20:23] offset:23040
	s_waitcnt vmcnt(5)
	ds_write_b128 v136, v[24:27] offset:27648
	s_waitcnt vmcnt(4)
	ds_write_b128 v136, v[28:31] offset:32256
	s_waitcnt vmcnt(3)
	ds_write_b128 v136, v[32:35] offset:36864
	s_waitcnt vmcnt(2)
	ds_write_b128 v136, v[36:39] offset:41472
	s_waitcnt vmcnt(1)
	ds_write_b128 v136, v[40:43] offset:46080
	s_waitcnt vmcnt(0)
	ds_write_b128 v136, v[44:47] offset:50688
	v_mov_b32_e32 v0, 0
	v_mov_b32_e32 v1, v0
	v_mov_b32_e32 v2, v0
	v_mov_b32_e32 v3, v0
	v_mov_b32_e32 v4, v0
	v_mov_b32_e32 v5, v0
	v_mov_b32_e32 v6, v0
	v_mov_b32_e32 v7, v0
	v_mov_b32_e32 v8, v0
	v_mov_b32_e32 v9, v0
	v_mov_b32_e32 v10, v0
	v_mov_b32_e32 v11, v0
	v_mov_b32_e32 v12, v0
	v_mov_b32_e32 v13, v0
	v_mov_b32_e32 v14, v0
	v_mov_b32_e32 v15, v0
	v_mov_b32_e32 v16, v0
	v_mov_b32_e32 v17, v0
	v_mov_b32_e32 v18, v0
	v_mov_b32_e32 v19, v0
	v_mov_b32_e32 v20, v0
	v_mov_b32_e32 v21, v0
	v_mov_b32_e32 v22, v0
	v_mov_b32_e32 v23, v0
	v_mov_b32_e32 v24, v0
	v_mov_b32_e32 v25, v0
	v_mov_b32_e32 v26, v0
	v_mov_b32_e32 v27, v0
	v_mov_b32_e32 v28, v0
	v_mov_b32_e32 v29, v0
	v_mov_b32_e32 v30, v0
	v_mov_b32_e32 v31, v0
	v_mov_b32_e32 v32, v0
	v_mov_b32_e32 v33, v0
	v_mov_b32_e32 v34, v0
	v_mov_b32_e32 v35, v0
	v_mov_b32_e32 v36, v0
	v_mov_b32_e32 v37, v0
	v_mov_b32_e32 v38, v0
	v_mov_b32_e32 v39, v0
	v_mov_b32_e32 v40, v0
	v_mov_b32_e32 v41, v0
	v_mov_b32_e32 v42, v0
	v_mov_b32_e32 v43, v0
	v_mov_b32_e32 v44, v0
	v_mov_b32_e32 v45, v0
	v_mov_b32_e32 v46, v0
	v_mov_b32_e32 v47, v0
	v_mov_b32_e32 v48, v0
	v_mov_b32_e32 v49, v0
	v_mov_b32_e32 v50, v0
	v_mov_b32_e32 v51, v0
	v_mov_b32_e32 v52, v0
	v_mov_b32_e32 v53, v0
	v_mov_b32_e32 v54, v0
	v_mov_b32_e32 v55, v0
	v_mov_b32_e32 v56, v0
	v_mov_b32_e32 v57, v0
	v_mov_b32_e32 v58, v0
	v_mov_b32_e32 v59, v0
; #define MFMA(a, b, c) __builtin_amdgcn_mfma_f32_32x32x16_bf16((a), (b), (c), 0, 0, 0)
; template <bool SWAP, bool SSQ, class AF>
; DI void gemm_main(AF asrc, int m0, const u16* __restrict__ Bw, int ldb, int K, char* smem,
;                   f32x16 (&acc)[4][2], float ssq_eps, float (&rs)[4]) {
;     ...
;   for (int mi = 0; mi < 4; ++mi)
; #pragma unroll
;     for (int ni = 0; ni < 2; ++ni)
; #pragma unroll
;       for (int i = 0; i < 16; ++i) acc[mi][ni][i] = 0.f;
;     ...
;   for (int kt = 0; kt < nkt; ++kt) {
;     if (kt + 1 < nkt) gload(kt + 1);
;     __builtin_amdgcn_sched_barrier(0);
;     {
;       bf16x8 ar[3], br[2][2];
;       ar[0] = *(const bf16x8*)(pA);
;       ar[1] = *(const bf16x8*)(pA + 32 * 144);
;       br[0][0] = *(const bf16x8*)(pB);
;       br[0][1] = *(const bf16x8*)(pB + 32 * 144);
;       __builtin_amdgcn_sched_group_barrier(0x100, 4, 0);
; #pragma unroll
;       for (int t = 0; t < 16; ++t) {
;         const int ks = t >> 2, mi = t & 3;
;         if (t + 2 < 16) {
;           ar[(t + 2) % 3] = *(const bf16x8*)(pA + ((t + 2) & 3) * (32 * 144) + ((t + 2) >> 2) * 32);
;           if (mi == 1 && ks + 1 < 4) {
;             br[(ks + 1) & 1][0] = *(const bf16x8*)(pB + (ks + 1) * 32);
;             br[(ks + 1) & 1][1] = *(const bf16x8*)(pB + 32 * 144 + (ks + 1) * 32);
;             __builtin_amdgcn_sched_group_barrier(0x100, 3, 0);
;           } else {
;             __builtin_amdgcn_sched_group_barrier(0x100, 1, 0);
;           }
;         }
;         acc[mi][0] = SWAP ? MFMA(br[ks & 1][0], ar[t % 3], acc[mi][0]) : MFMA(ar[t % 3], br[ks & 1][0], acc[mi][0]);
;         acc[mi][1] = SWAP ? MFMA(br[ks & 1][1], ar[t % 3], acc[mi][1]) : MFMA(ar[t % 3], br[ks & 1][1], acc[mi][1]);
;         __builtin_amdgcn_sched_group_barrier(0x008, 2, 0);
	v_mov_b32_e32 v60, v0
	v_mov_b32_e32 v61, v0
	v_mov_b32_e32 v62, v0
	v_mov_b32_e32 v63, v0
	v_mov_b32_e32 v64, v0
	v_mov_b32_e32 v65, v0
	v_mov_b32_e32 v66, v0
	v_mov_b32_e32 v67, v0
	v_mov_b32_e32 v68, v0
	v_mov_b32_e32 v69, v0
	v_mov_b32_e32 v70, v0
	v_mov_b32_e32 v71, v0
	v_mov_b32_e32 v72, v0
	v_mov_b32_e32 v73, v0
	v_mov_b32_e32 v74, v0
	v_mov_b32_e32 v75, v0
	v_mov_b32_e32 v76, v0
	v_mov_b32_e32 v77, v0
	v_mov_b32_e32 v78, v0
	v_mov_b32_e32 v79, v0
	v_mov_b32_e32 v80, v0
	v_mov_b32_e32 v81, v0
	v_mov_b32_e32 v82, v0
	v_mov_b32_e32 v83, v0
	v_mov_b32_e32 v84, v0
	v_mov_b32_e32 v85, v0
	v_mov_b32_e32 v86, v0
	v_mov_b32_e32 v87, v0
	v_mov_b32_e32 v88, v0
	v_mov_b32_e32 v89, v0
	v_mov_b32_e32 v90, v0
	v_mov_b32_e32 v91, v0
	v_mov_b32_e32 v92, v0
	v_mov_b32_e32 v93, v0
	v_mov_b32_e32 v94, v0
	v_mov_b32_e32 v95, v0
	v_mov_b32_e32 v96, v0
	v_mov_b32_e32 v97, v0
	v_mov_b32_e32 v98, v0
	v_mov_b32_e32 v99, v0
	v_mov_b32_e32 v100, v0
	v_mov_b32_e32 v101, v0
	v_mov_b32_e32 v102, v0
	v_mov_b32_e32 v103, v0
	v_mov_b32_e32 v104, v0
	v_mov_b32_e32 v105, v0
	v_mov_b32_e32 v106, v0
	v_mov_b32_e32 v107, v0
	v_mov_b32_e32 v108, v0
	v_mov_b32_e32 v109, v0
	v_mov_b32_e32 v110, v0
	v_mov_b32_e32 v111, v0
	v_mov_b32_e32 v112, v0
	v_mov_b32_e32 v113, v0
	v_mov_b32_e32 v114, v0
	v_mov_b32_e32 v115, v0
	v_mov_b32_e32 v116, v0
	v_mov_b32_e32 v117, v0
	v_mov_b32_e32 v118, v0
	v_mov_b32_e32 v119, v0
	v_mov_b32_e32 v120, v0
	v_mov_b32_e32 v121, v0
	v_mov_b32_e32 v122, v0
	v_mov_b32_e32 v123, v0
	v_mov_b32_e32 v124, v0
	v_mov_b32_e32 v125, v0
	v_mov_b32_e32 v126, v0
	v_mov_b32_e32 v127, v0
	s_waitcnt lgkmcnt(0)
	s_barrier
	v_readfirstlane_b32 s9, v184
	v_readfirstlane_b32 s34, v138
	v_readfirstlane_b32 s35, v139
	v_readfirstlane_b32 s100, v140
	v_readfirstlane_b32 s101, v141
	v_subrev_u32_e32 v198, s9, v184
	s_add_u32 s34, s34, 0x80
	s_addc_u32 s35, s35, 0
	s_add_u32 s36, s34, 0x80000
	s_addc_u32 s37, s35, 0
	s_add_u32 s100, s100, 0x80
	s_addc_u32 s101, s101, 0
	v_add_u32_e32 v199, 0x20000, v198
	v_add_u32_e32 v217, 0x40000, v198
	v_add_u32_e32 v250, 0x60000, v198
	ds_read_b128 v[218:221], v142 offset:36864
	ds_read_b128 v[222:225], v142 offset:41472
	ds_read_b128 v[226:229], v137
	ds_read_b128 v[230:233], v137 offset:4608
	ds_read_b128 v[234:237], v137 offset:9216
.LBB0_588:
	ds_read_b128 v[238:241], v137 offset:13824
	global_load_dwordx4 v[144:147], v198, s[34:35]
	s_waitcnt lgkmcnt(3)
	v_mfma_f32_32x32x16_bf16 v[112:127], v[218:221], v[226:229], v[112:127]
	v_mfma_f32_32x32x16_bf16 v[96:111], v[222:225], v[226:229], v[96:111]
	ds_read_b128 v[226:229], v142 offset:36896
	ds_read_b128 v[242:245], v142 offset:41504
	global_load_dwordx4 v[150:153], v199, s[34:35]
	global_load_dwordx4 v[154:157], v217, s[34:35]
	s_waitcnt lgkmcnt(4)
	v_mfma_f32_32x32x16_bf16 v[80:95], v[218:221], v[230:233], v[80:95]
	v_mfma_f32_32x32x16_bf16 v[64:79], v[222:225], v[230:233], v[64:79]
	ds_read_b128 v[230:233], v137 offset:32
	global_load_dwordx4 v[158:161], v250, s[34:35]
	s_waitcnt lgkmcnt(4)
	v_mfma_f32_32x32x16_bf16 v[48:63], v[218:221], v[234:237], v[48:63]
	v_mfma_f32_32x32x16_bf16 v[32:47], v[222:225], v[234:237], v[32:47]
	ds_read_b128 v[234:237], v137 offset:4640
	global_load_dwordx4 v[162:165], v198, s[36:37]
	s_waitcnt lgkmcnt(4)
	v_mfma_f32_32x32x16_bf16 v[16:31], v[218:221], v[238:241], v[16:31]
	v_mfma_f32_32x32x16_bf16 v[0:15], v[222:225], v[238:241], v[0:15]
	ds_read_b128 v[218:221], v137 offset:9248
	ds_read_b128 v[222:225], v137 offset:13856
	global_load_dwordx4 v[166:169], v199, s[36:37]
	s_waitcnt lgkmcnt(3)
	v_mfma_f32_32x32x16_bf16 v[112:127], v[226:229], v[230:233], v[112:127]
	v_mfma_f32_32x32x16_bf16 v[96:111], v[242:245], v[230:233], v[96:111]
	ds_read_b128 v[230:233], v142 offset:36928
	ds_read_b128 v[202:205], v142 offset:41536
	global_load_dwordx4 v[170:173], v217, s[36:37]
	s_waitcnt lgkmcnt(4)
	v_mfma_f32_32x32x16_bf16 v[80:95], v[226:229], v[234:237], v[80:95]
	v_mfma_f32_32x32x16_bf16 v[64:79], v[242:245], v[234:237], v[64:79]
	ds_read_b128 v[234:237], v137 offset:64
	ds_read_b128 v[206:209], v137 offset:4672
	global_load_dwordx4 v[174:177], v250, s[36:37]
	s_waitcnt lgkmcnt(5)
	v_mfma_f32_32x32x16_bf16 v[48:63], v[226:229], v[218:221], v[48:63]
	v_mfma_f32_32x32x16_bf16 v[32:47], v[242:245], v[218:221], v[32:47]
	ds_read_b128 v[218:221], v137 offset:9280
	global_load_dwordx4 v[178:181], v198, s[100:101]
	s_waitcnt lgkmcnt(5)
	v_mfma_f32_32x32x16_bf16 v[16:31], v[226:229], v[222:225], v[16:31]
	v_mfma_f32_32x32x16_bf16 v[0:15], v[242:245], v[222:225], v[0:15]
	ds_read_b128 v[226:229], v137 offset:13888
	ds_read_b128 v[246:249], v142 offset:36960
	ds_read_b128 v[238:241], v142 offset:41568
	global_load_dwordx4 v[186:189], v199, s[100:101]
	s_waitcnt lgkmcnt(5)
	v_mfma_f32_32x32x16_bf16 v[112:127], v[230:233], v[234:237], v[112:127]
	v_mfma_f32_32x32x16_bf16 v[96:111], v[202:205], v[234:237], v[96:111]
	ds_read_b128 v[222:225], v137 offset:96
	ds_read_b128 v[234:237], v137 offset:4704
	global_load_dwordx4 v[190:193], v217, s[100:101]
	s_waitcnt lgkmcnt(6)
	v_mfma_f32_32x32x16_bf16 v[80:95], v[230:233], v[206:209], v[80:95]
	v_mfma_f32_32x32x16_bf16 v[64:79], v[202:205], v[206:209], v[64:79]
	ds_read_b128 v[242:245], v137 offset:9312
	ds_read_b128 v[206:209], v137 offset:13920
	global_load_dwordx4 v[194:197], v250, s[100:101]
	s_waitcnt lgkmcnt(0)
	s_barrier
; #define MFMA(a, b, c) __builtin_amdgcn_mfma_f32_32x32x16_bf16((a), (b), (c), 0, 0, 0)
; template <bool SWAP, bool SSQ, class AF>
; DI void gemm_main(AF asrc, int m0, const u16* __restrict__ Bw, int ldb, int K, char* smem,
;                   f32x16 (&acc)[4][2], float ssq_eps, float (&rs)[4]) {
;     ...
;       for (int t = 0; t < 16; ++t) {
;         const int ks = t >> 2, mi = t & 3;
;         if (t + 2 < 16) {
;           ar[(t + 2) % 3] = *(const bf16x8*)(pA + ((t + 2) & 3) * (32 * 144) + ((t + 2) >> 2) * 32);
;           if (mi == 1 && ks + 1 < 4) {
;             br[(ks + 1) & 1][0] = *(const bf16x8*)(pB + (ks + 1) * 32);
;             br[(ks + 1) & 1][1] = *(const bf16x8*)(pB + 32 * 144 + (ks + 1) * 32);
;             __builtin_amdgcn_sched_group_barrier(0x100, 3, 0);
;           } else {
;             __builtin_amdgcn_sched_group_barrier(0x100, 1, 0);
;           }
;         }
;         acc[mi][0] = SWAP ? MFMA(br[ks & 1][0], ar[t % 3], acc[mi][0]) : MFMA(ar[t % 3], br[ks & 1][0], acc[mi][0]);
;         acc[mi][1] = SWAP ? MFMA(br[ks & 1][1], ar[t % 3], acc[mi][1]) : MFMA(ar[t % 3], br[ks & 1][1], acc[mi][1]);
;         __builtin_amdgcn_sched_group_barrier(0x008, 2, 0);
;         if (SSQ) {
;           u32x4 u = __builtin_bit_cast(u32x4, ar[t % 3]);
; #pragma unroll
;           for (int j = 0; j < 4; ++j) rs[mi] = dot2bf(u[j], rs[mi]);
;         }
;       }
;     }
;     __syncthreads();
;     if (kt + 1 < nkt) sstore();
;     __syncthreads();
	v_mfma_f32_32x32x16_bf16 v[48:63], v[230:233], v[218:221], v[48:63]
	v_mfma_f32_32x32x16_bf16 v[32:47], v[202:205], v[218:221], v[32:47]
	s_waitcnt vmcnt(11)
	ds_write_b128 v136, v[144:147]
	s_waitcnt vmcnt(10)
	ds_write_b128 v136, v[150:153] offset:4608
	s_waitcnt vmcnt(9)
	ds_write_b128 v136, v[154:157] offset:9216
	v_mfma_f32_32x32x16_bf16 v[16:31], v[230:233], v[226:229], v[16:31]
	v_mfma_f32_32x32x16_bf16 v[0:15], v[202:205], v[226:229], v[0:15]
	s_waitcnt vmcnt(8)
	ds_write_b128 v136, v[158:161] offset:13824
	s_waitcnt vmcnt(7)
	ds_write_b128 v136, v[162:165] offset:18432
	s_waitcnt vmcnt(6)
	ds_write_b128 v136, v[166:169] offset:23040
	v_mfma_f32_32x32x16_bf16 v[112:127], v[246:249], v[222:225], v[112:127]
	v_mfma_f32_32x32x16_bf16 v[96:111], v[238:241], v[222:225], v[96:111]
	s_waitcnt vmcnt(5)
	ds_write_b128 v136, v[170:173] offset:27648
	s_waitcnt vmcnt(4)
	ds_write_b128 v136, v[174:177] offset:32256
	s_waitcnt vmcnt(3)
	ds_write_b128 v136, v[178:181] offset:36864
	v_mfma_f32_32x32x16_bf16 v[80:95], v[246:249], v[234:237], v[80:95]
	v_mfma_f32_32x32x16_bf16 v[64:79], v[238:241], v[234:237], v[64:79]
	s_waitcnt vmcnt(2)
	ds_write_b128 v136, v[186:189] offset:41472
	s_waitcnt vmcnt(1)
	ds_write_b128 v136, v[190:193] offset:46080
	s_waitcnt vmcnt(0)
	ds_write_b128 v136, v[194:197] offset:50688
	s_waitcnt lgkmcnt(0)
	s_barrier
	ds_read_b128 v[218:221], v142 offset:36864
	ds_read_b128 v[222:225], v142 offset:41472
	ds_read_b128 v[226:229], v137
	ds_read_b128 v[230:233], v137 offset:4608
	ds_read_b128 v[234:237], v137 offset:9216
	v_mfma_f32_32x32x16_bf16 v[48:63], v[246:249], v[242:245], v[48:63]
	v_mfma_f32_32x32x16_bf16 v[32:47], v[238:241], v[242:245], v[32:47]
	v_mfma_f32_32x32x16_bf16 v[16:31], v[246:249], v[206:209], v[16:31]
	v_mfma_f32_32x32x16_bf16 v[0:15], v[238:241], v[206:209], v[0:15]
	s_add_u32 s34, s34, 0x80
	s_addc_u32 s35, s35, 0
	s_add_u32 s36, s36, 0x80
	s_addc_u32 s37, s37, 0
	s_add_u32 s100, s100, 0x80
	s_addc_u32 s101, s101, 0
	s_add_u32 s12, s12, 0x80
	s_cmpk_lg_i32 s12, 0xf80
	s_cbranch_scc1 .LBB0_588
	ds_read_b128 v[138:141], v142 offset:36864
	ds_read_b128 v[154:157], v142 offset:41472
	ds_read_b128 v[144:147], v137
	ds_read_b128 v[150:153], v137 offset:4608
	ds_read_b128 v[158:161], v137 offset:9216
	s_or_b32 s64, s8, s56
	s_cmpk_gt_i32 s64, 0x153f
	s_waitcnt lgkmcnt(2)
	v_mfma_f32_32x32x16_bf16 v[112:127], v[138:141], v[144:147], v[112:127]
	v_mfma_f32_32x32x16_bf16 v[96:111], v[154:157], v[144:147], v[96:111]
	ds_read_b128 v[162:165], v142 offset:36896
	ds_read_b128 v[166:169], v142 offset:41504
	ds_read_b128 v[144:147], v137 offset:13824
	s_waitcnt lgkmcnt(4)
	v_mfma_f32_32x32x16_bf16 v[80:95], v[138:141], v[150:153], v[80:95]
	v_mfma_f32_32x32x16_bf16 v[64:79], v[154:157], v[150:153], v[64:79]
	ds_read_b128 v[150:153], v137 offset:32
	s_waitcnt lgkmcnt(4)
	v_mfma_f32_32x32x16_bf16 v[48:63], v[138:141], v[158:161], v[48:63]
	v_mfma_f32_32x32x16_bf16 v[32:47], v[154:157], v[158:161], v[32:47]
	ds_read_b128 v[158:161], v137 offset:4640
	s_waitcnt lgkmcnt(2)
	v_mfma_f32_32x32x16_bf16 v[16:31], v[138:141], v[144:147], v[16:31]
	v_mfma_f32_32x32x16_bf16 v[0:15], v[154:157], v[144:147], v[0:15]
	ds_read_b128 v[138:141], v137 offset:9248
	s_waitcnt lgkmcnt(2)
	v_mfma_f32_32x32x16_bf16 v[112:127], v[162:165], v[150:153], v[112:127]
	v_mfma_f32_32x32x16_bf16 v[96:111], v[166:169], v[150:153], v[96:111]
	ds_read_b128 v[150:153], v142 offset:36928
	ds_read_b128 v[154:157], v142 offset:41536
	ds_read_b128 v[144:147], v137 offset:13856
	s_waitcnt lgkmcnt(4)
	v_mfma_f32_32x32x16_bf16 v[80:95], v[162:165], v[158:161], v[80:95]
	v_mfma_f32_32x32x16_bf16 v[64:79], v[166:169], v[158:161], v[64:79]
	ds_read_b128 v[158:161], v137 offset:64
	s_waitcnt lgkmcnt(4)
	v_mfma_f32_32x32x16_bf16 v[48:63], v[162:165], v[138:141], v[48:63]
	v_mfma_f32_32x32x16_bf16 v[32:47], v[166:169], v[138:141], v[32:47]
	ds_read_b128 v[138:141], v137 offset:4672
	s_waitcnt lgkmcnt(2)
	v_mfma_f32_32x32x16_bf16 v[16:31], v[162:165], v[144:147], v[16:31]
	v_mfma_f32_32x32x16_bf16 v[0:15], v[166:169], v[144:147], v[0:15]
	ds_read_b128 v[144:147], v137 offset:9280
	s_waitcnt lgkmcnt(2)
	v_mfma_f32_32x32x16_bf16 v[112:127], v[150:153], v[158:161], v[112:127]
	v_mfma_f32_32x32x16_bf16 v[96:111], v[154:157], v[158:161], v[96:111]
	ds_read_b128 v[162:165], v142 offset:36960
	ds_read_b128 v[166:169], v142 offset:41568
	ds_read_b128 v[158:161], v137 offset:13888
	s_waitcnt lgkmcnt(4)
	v_mfma_f32_32x32x16_bf16 v[80:95], v[150:153], v[138:141], v[80:95]
	v_mfma_f32_32x32x16_bf16 v[64:79], v[154:157], v[138:141], v[64:79]
	ds_read_b128 v[138:141], v137 offset:96
	s_waitcnt lgkmcnt(4)
	v_mfma_f32_32x32x16_bf16 v[48:63], v[150:153], v[144:147], v[48:63]
	v_mfma_f32_32x32x16_bf16 v[32:47], v[154:157], v[144:147], v[32:47]
	ds_read_b128 v[142:145], v137 offset:4704
	s_waitcnt lgkmcnt(2)
	v_mfma_f32_32x32x16_bf16 v[16:31], v[150:153], v[158:161], v[16:31]
	v_mfma_f32_32x32x16_bf16 v[0:15], v[154:157], v[158:161], v[0:15]
	ds_read_b128 v[150:153], v137 offset:9312
	s_waitcnt lgkmcnt(2)
	v_mfma_f32_32x32x16_bf16 v[112:127], v[162:165], v[138:141], v[112:127]
	v_mfma_f32_32x32x16_bf16 v[96:111], v[166:169], v[138:141], v[96:111]
	ds_read_b128 v[136:139], v137 offset:13920
	s_waitcnt lgkmcnt(0)
	s_barrier
; DI void phase_inproj(const Params& p, const GroupP& g, int l, char* smem, int vb) {
;     ...
;     if (l == 1) {
;       const float* sq = p.rowsq + (size_t)4 * 50432 + g.seq0 + m0 + wm * 128 + lr;
; #pragma unroll
;       for (int mi = 0; mi < 4; ++mi) {
;         const float r = __builtin_amdgcn_rsqf(sq[mi * 32] * (1.f / DM) + 1e-6f);
; #pragma unroll
;         for (int ni = 0; ni < 2; ++ni)
; #pragma unroll
;           for (int i = 0; i < 16; ++i) acc[mi][ni][i] *= r;
;       }
;     }
	s_barrier
	v_mfma_f32_32x32x16_bf16 v[80:95], v[162:165], v[142:145], v[80:95]
	v_mfma_f32_32x32x16_bf16 v[64:79], v[166:169], v[142:145], v[64:79]
	v_mfma_f32_32x32x16_bf16 v[48:63], v[162:165], v[150:153], v[48:63]
	v_mfma_f32_32x32x16_bf16 v[32:47], v[166:169], v[150:153], v[32:47]
	v_mfma_f32_32x32x16_bf16 v[16:31], v[162:165], v[136:139], v[16:31]
	v_mfma_f32_32x32x16_bf16 v[0:15], v[166:169], v[136:139], v[0:15]
	s_cbranch_scc1 .LBB0_583
	v_readlane_b32 s12, v254, 31
	v_readlane_b32 s13, v254, 32
	s_andn2_b64 vcc, exec, s[12:13]
	s_cbranch_vccnz .LBB0_592
	v_lshl_add_u64 v[136:137], s[10:11], 2, v[132:133]
	global_load_dword v138, v[136:137], off
	s_waitcnt vmcnt(0)
	v_fmamk_f32 v138, v138, 0x3a000000, v215
	v_rsq_f32_e32 v138, v138
	s_nop 0
	v_pk_mul_f32 v[126:127], v[126:127], v[138:139] op_sel_hi:[1,0]
	v_pk_mul_f32 v[124:125], v[124:125], v[138:139] op_sel_hi:[1,0]
	v_pk_mul_f32 v[122:123], v[122:123], v[138:139] op_sel_hi:[1,0]
	v_pk_mul_f32 v[120:121], v[120:121], v[138:139] op_sel_hi:[1,0]
	v_pk_mul_f32 v[118:119], v[118:119], v[138:139] op_sel_hi:[1,0]
	v_pk_mul_f32 v[116:117], v[116:117], v[138:139] op_sel_hi:[1,0]
	v_pk_mul_f32 v[114:115], v[114:115], v[138:139] op_sel_hi:[1,0]
	v_pk_mul_f32 v[112:113], v[112:113], v[138:139] op_sel_hi:[1,0]
	v_pk_mul_f32 v[110:111], v[110:111], v[138:139] op_sel_hi:[1,0]
	v_pk_mul_f32 v[108:109], v[108:109], v[138:139] op_sel_hi:[1,0]
	v_pk_mul_f32 v[106:107], v[106:107], v[138:139] op_sel_hi:[1,0]
	v_pk_mul_f32 v[104:105], v[104:105], v[138:139] op_sel_hi:[1,0]
	v_pk_mul_f32 v[102:103], v[102:103], v[138:139] op_sel_hi:[1,0]
	v_pk_mul_f32 v[100:101], v[100:101], v[138:139] op_sel_hi:[1,0]
	v_pk_mul_f32 v[98:99], v[98:99], v[138:139] op_sel_hi:[1,0]
	v_pk_mul_f32 v[96:97], v[96:97], v[138:139] op_sel_hi:[1,0]
	global_load_dword v138, v[136:137], off offset:128
	s_waitcnt vmcnt(0)
	v_fmamk_f32 v138, v138, 0x3a000000, v215
	v_rsq_f32_e32 v138, v138
	s_nop 0
	v_pk_mul_f32 v[94:95], v[94:95], v[138:139] op_sel_hi:[1,0]
	v_pk_mul_f32 v[92:93], v[92:93], v[138:139] op_sel_hi:[1,0]
	v_pk_mul_f32 v[90:91], v[90:91], v[138:139] op_sel_hi:[1,0]
	v_pk_mul_f32 v[88:89], v[88:89], v[138:139] op_sel_hi:[1,0]
	v_pk_mul_f32 v[86:87], v[86:87], v[138:139] op_sel_hi:[1,0]
	v_pk_mul_f32 v[84:85], v[84:85], v[138:139] op_sel_hi:[1,0]
	v_pk_mul_f32 v[82:83], v[82:83], v[138:139] op_sel_hi:[1,0]
	v_pk_mul_f32 v[80:81], v[80:81], v[138:139] op_sel_hi:[1,0]
	v_pk_mul_f32 v[78:79], v[78:79], v[138:139] op_sel_hi:[1,0]
	v_pk_mul_f32 v[76:77], v[76:77], v[138:139] op_sel_hi:[1,0]
	v_pk_mul_f32 v[74:75], v[74:75], v[138:139] op_sel_hi:[1,0]
	v_pk_mul_f32 v[72:73], v[72:73], v[138:139] op_sel_hi:[1,0]
	v_pk_mul_f32 v[70:71], v[70:71], v[138:139] op_sel_hi:[1,0]
	v_pk_mul_f32 v[68:69], v[68:69], v[138:139] op_sel_hi:[1,0]
	v_pk_mul_f32 v[66:67], v[66:67], v[138:139] op_sel_hi:[1,0]
	v_pk_mul_f32 v[64:65], v[64:65], v[138:139] op_sel_hi:[1,0]
	global_load_dword v138, v[136:137], off offset:256
	s_waitcnt vmcnt(0)
	v_fmamk_f32 v138, v138, 0x3a000000, v215
	global_load_dword v136, v[136:137], off offset:384
	v_rsq_f32_e32 v138, v138
	s_waitcnt vmcnt(0)
	v_fmamk_f32 v136, v136, 0x3a000000, v215
	v_rsq_f32_e32 v136, v136
	v_pk_mul_f32 v[62:63], v[62:63], v[138:139] op_sel_hi:[1,0]
	v_pk_mul_f32 v[60:61], v[60:61], v[138:139] op_sel_hi:[1,0]
	v_pk_mul_f32 v[58:59], v[58:59], v[138:139] op_sel_hi:[1,0]
	v_pk_mul_f32 v[56:57], v[56:57], v[138:139] op_sel_hi:[1,0]
	v_pk_mul_f32 v[54:55], v[54:55], v[138:139] op_sel_hi:[1,0]
	v_pk_mul_f32 v[52:53], v[52:53], v[138:139] op_sel_hi:[1,0]
	v_pk_mul_f32 v[50:51], v[50:51], v[138:139] op_sel_hi:[1,0]
	v_pk_mul_f32 v[48:49], v[48:49], v[138:139] op_sel_hi:[1,0]
	v_pk_mul_f32 v[46:47], v[46:47], v[138:139] op_sel_hi:[1,0]
	v_pk_mul_f32 v[44:45], v[44:45], v[138:139] op_sel_hi:[1,0]
	v_pk_mul_f32 v[42:43], v[42:43], v[138:139] op_sel_hi:[1,0]
	v_pk_mul_f32 v[40:41], v[40:41], v[138:139] op_sel_hi:[1,0]
	v_pk_mul_f32 v[38:39], v[38:39], v[138:139] op_sel_hi:[1,0]
	v_pk_mul_f32 v[36:37], v[36:37], v[138:139] op_sel_hi:[1,0]
	v_pk_mul_f32 v[34:35], v[34:35], v[138:139] op_sel_hi:[1,0]
	v_pk_mul_f32 v[32:33], v[32:33], v[138:139] op_sel_hi:[1,0]
	v_pk_mul_f32 v[30:31], v[30:31], v[136:137] op_sel_hi:[1,0]
	v_pk_mul_f32 v[28:29], v[28:29], v[136:137] op_sel_hi:[1,0]
	v_pk_mul_f32 v[26:27], v[26:27], v[136:137] op_sel_hi:[1,0]
	v_pk_mul_f32 v[24:25], v[24:25], v[136:137] op_sel_hi:[1,0]
	v_pk_mul_f32 v[22:23], v[22:23], v[136:137] op_sel_hi:[1,0]
	v_pk_mul_f32 v[20:21], v[20:21], v[136:137] op_sel_hi:[1,0]
	v_pk_mul_f32 v[18:19], v[18:19], v[136:137] op_sel_hi:[1,0]
	v_pk_mul_f32 v[16:17], v[16:17], v[136:137] op_sel_hi:[1,0]
	v_pk_mul_f32 v[14:15], v[14:15], v[136:137] op_sel_hi:[1,0]
	v_pk_mul_f32 v[12:13], v[12:13], v[136:137] op_sel_hi:[1,0]
	v_pk_mul_f32 v[10:11], v[10:11], v[136:137] op_sel_hi:[1,0]
	v_pk_mul_f32 v[8:9], v[8:9], v[136:137] op_sel_hi:[1,0]
	v_pk_mul_f32 v[6:7], v[6:7], v[136:137] op_sel_hi:[1,0]
	v_pk_mul_f32 v[4:5], v[4:5], v[136:137] op_sel_hi:[1,0]
	v_pk_mul_f32 v[2:3], v[2:3], v[136:137] op_sel_hi:[1,0]
	v_pk_mul_f32 v[0:1], v[0:1], v[136:137] op_sel_hi:[1,0]
